# RWKV scan: grouped LDS loads 1 step ahead, b64 v-read, bank-masked reduce-scatter; LRU recurrence batched 8 steps per LDS round trip
# speedup vs baseline: 1.0347x; 1.0270x over previous
.LBB0_283:
	v_and_b32_e32 v39, 63, v132
	v_lshlrev_b32_e32 v0, 2, v132
	v_and_b32_e32 v37, 0xffffff00, v0
	v_lshlrev_b32_e32 v2, 2, v39
	v_add3_u32 v0, 0, v37, v2
	v_ashrrev_i32_e32 v40, 6, v132
	ds_read_b32 v3, v0
	v_lshlrev_b32_e32 v138, 8, v40
	v_add3_u32 v139, 0, v138, v2
	ds_read2st64_b32 v[136:137], v139 offset0:1 offset1:2
	s_add_i32 s24, 0, 0x10000
	s_waitcnt lgkmcnt(1)
	v_fma_f32 v135, v42, v3, v122
	ds_read_b32 v3, v139 offset:768
	s_movk_i32 s25, 0x90
	s_waitcnt lgkmcnt(1)
	v_fmac_f32_e32 v135, v43, v136
	v_fmac_f32_e32 v135, v44, v137
	v_mul_lo_u32 v40, v40, s25
	s_waitcnt lgkmcnt(0)
	v_fmac_f32_e32 v135, v45, v3
	v_add3_u32 v3, s24, v37, v2
	v_bfe_u32 v136, v135, 16, 1
	v_lshlrev_b32_e32 v39, 1, v39
	ds_write_b32 v3, v135
	v_add3_u32 v135, v135, v136, s97
	v_add3_u32 v136, s65, v40, v39
	ds_write_b16_d16_hi v136, v135
	v_add_u32_e32 v135, 0x800, v138
	v_add3_u32 v140, 0, v135, v2
	ds_read2st64_b32 v[136:137], v140 offset1:1
	v_add_u32_e32 v142, 0x1000, v138
	v_add3_u32 v143, 0, v142, v2
	v_add_u32_e32 v155, 0x1800, v138
	v_add3_u32 v156, 0, v155, v2
	s_waitcnt lgkmcnt(0)
	v_fma_f32 v141, v42, v136, v122
	v_fmac_f32_e32 v141, v43, v137
	ds_read2st64_b32 v[136:137], v140 offset0:2 offset1:3
	v_add_u32_e32 v158, 0x2000, v138
	v_add3_u32 v159, 0, v158, v2
	v_add_u32_e32 v161, 0x2800, v138
	v_add3_u32 v162, 0, v161, v2
	s_waitcnt lgkmcnt(0)
	v_fmac_f32_e32 v141, v44, v136
	v_fmac_f32_e32 v141, v45, v137
	v_add3_u32 v136, s24, v135, v2
	ds_write_b32 v136, v141
	v_bfe_u32 v136, v141, 16, 1
	v_add3_u32 v136, v141, v136, s97
	v_add_u32_e32 v141, 0x480, v40
	v_add3_u32 v137, s65, v141, v39
	ds_write_b16_d16_hi v137, v136
	ds_read2st64_b32 v[136:137], v143 offset1:1
	v_add_u32_e32 v164, 0x3000, v138
	v_add3_u32 v165, 0, v164, v2
	v_add_u32_e32 v138, 0x3800, v138
	v_add3_u32 v167, 0, v138, v2
	s_waitcnt lgkmcnt(0)
	v_fma_f32 v154, v42, v136, v122
	v_fmac_f32_e32 v154, v43, v137
	ds_read2st64_b32 v[136:137], v143 offset0:2 offset1:3
	s_add_i32 s25, 0, 0x14000
	v_add3_u32 v37, s25, v37, v2
	v_add3_u32 v135, s25, v135, v2
	v_and_b32_e32 v38, 15, v36
	s_waitcnt lgkmcnt(0)
	v_fmac_f32_e32 v154, v44, v136
	v_fmac_f32_e32 v154, v45, v137
	v_add3_u32 v136, s24, v142, v2
	ds_write_b32 v136, v154
	v_bfe_u32 v136, v154, 16, 1
	v_add3_u32 v136, v154, v136, s97
	v_add_u32_e32 v154, 0x900, v40
	v_add3_u32 v137, s65, v154, v39
	ds_write_b16_d16_hi v137, v136
	ds_read2st64_b32 v[136:137], v156 offset1:1
	s_andn2_b64 vcc, exec, s[46:47]
	s_waitcnt lgkmcnt(0)
	v_fma_f32 v157, v42, v136, v122
	v_fmac_f32_e32 v157, v43, v137
	ds_read2st64_b32 v[136:137], v156 offset0:2 offset1:3
	s_waitcnt lgkmcnt(0)
	v_fmac_f32_e32 v157, v44, v136
	v_fmac_f32_e32 v157, v45, v137
	v_add3_u32 v136, s24, v155, v2
	ds_write_b32 v136, v157
	v_bfe_u32 v136, v157, 16, 1
	v_add3_u32 v136, v157, v136, s97
	v_add_u32_e32 v157, 0xd80, v40
	v_add3_u32 v137, s65, v157, v39
	ds_write_b16_d16_hi v137, v136
	ds_read2st64_b32 v[136:137], v159 offset1:1
	s_waitcnt lgkmcnt(0)
	v_fma_f32 v160, v42, v136, v122
	v_fmac_f32_e32 v160, v43, v137
	ds_read2st64_b32 v[136:137], v159 offset0:2 offset1:3
	s_waitcnt lgkmcnt(0)
	v_fmac_f32_e32 v160, v44, v136
	v_fmac_f32_e32 v160, v45, v137
	v_add3_u32 v136, s24, v158, v2
	ds_write_b32 v136, v160
	v_bfe_u32 v136, v160, 16, 1
	v_add3_u32 v136, v160, v136, s97
	v_add_u32_e32 v160, 0x1200, v40
	v_add3_u32 v137, s65, v160, v39
	ds_write_b16_d16_hi v137, v136
	ds_read2st64_b32 v[136:137], v162 offset1:1
	s_waitcnt lgkmcnt(0)
	v_fma_f32 v163, v42, v136, v122
	v_fmac_f32_e32 v163, v43, v137
	ds_read2st64_b32 v[136:137], v162 offset0:2 offset1:3
	s_waitcnt lgkmcnt(0)
	v_fmac_f32_e32 v163, v44, v136
	v_fmac_f32_e32 v163, v45, v137
	v_add3_u32 v136, s24, v161, v2
	ds_write_b32 v136, v163
	v_bfe_u32 v136, v163, 16, 1
	v_add3_u32 v136, v163, v136, s97
	v_add_u32_e32 v163, 0x1680, v40
	v_add3_u32 v137, s65, v163, v39
	ds_write_b16_d16_hi v137, v136
	ds_read2st64_b32 v[136:137], v165 offset1:1
	s_waitcnt lgkmcnt(0)
	v_fma_f32 v166, v42, v136, v122
	v_fmac_f32_e32 v166, v43, v137
	ds_read2st64_b32 v[136:137], v165 offset0:2 offset1:3
	s_waitcnt lgkmcnt(0)
	v_fmac_f32_e32 v166, v44, v136
	v_fmac_f32_e32 v166, v45, v137
	v_add3_u32 v136, s24, v164, v2
	ds_write_b32 v136, v166
	v_bfe_u32 v136, v166, 16, 1
	v_add3_u32 v136, v166, v136, s97
	v_add_u32_e32 v166, 0x1b00, v40
	v_add3_u32 v137, s65, v166, v39
	ds_write_b16_d16_hi v137, v136
	ds_read2st64_b32 v[136:137], v167 offset1:1
	s_waitcnt lgkmcnt(0)
	v_fma_f32 v168, v42, v136, v122
	v_fmac_f32_e32 v168, v43, v137
	ds_read2st64_b32 v[136:137], v167 offset0:2 offset1:3
	s_waitcnt lgkmcnt(0)
	v_fmac_f32_e32 v168, v44, v136
	v_fmac_f32_e32 v168, v45, v137
	v_add3_u32 v136, s24, v138, v2
	ds_write_b32 v136, v168
	v_bfe_u32 v136, v168, 16, 1
	v_add3_u32 v136, v168, v136, s97
	v_add_u32_e32 v168, 0x1f80, v40
	v_add3_u32 v137, s65, v168, v39
	ds_write_b16_d16_hi v137, v136
	ds_read_b32 v136, v0 offset:17408
	v_add3_u32 v40, s4, v40, v39
	s_waitcnt lgkmcnt(0)
	v_fma_f32 v169, v123, v136, v127
	ds_read2st64_b32 v[136:137], v139 offset0:69 offset1:70
	s_waitcnt lgkmcnt(0)
	v_fmac_f32_e32 v169, v124, v136
	ds_read_b32 v136, v139 offset:18176
	v_fmac_f32_e32 v169, v125, v137
	s_waitcnt lgkmcnt(0)
	v_fmac_f32_e32 v169, v126, v136
	v_bfe_u32 v136, v169, 16, 1
	ds_write_b32 v37, v169
	v_add3_u32 v136, v169, v136, s97
	ds_write_b16_d16_hi v40, v136
	ds_read2st64_b32 v[136:137], v140 offset0:68 offset1:69
	s_waitcnt lgkmcnt(0)
	v_fma_f32 v40, v123, v136, v127
	v_fmac_f32_e32 v40, v124, v137
	ds_read2st64_b32 v[136:137], v140 offset0:70 offset1:71
	s_waitcnt lgkmcnt(0)
	v_fmac_f32_e32 v40, v125, v136
	v_fmac_f32_e32 v40, v126, v137
	ds_read2st64_b32 v[136:137], v143 offset0:68 offset1:69
	ds_write_b32 v135, v40
	v_bfe_u32 v135, v40, 16, 1
	v_add3_u32 v40, v40, v135, s97
	v_add3_u32 v135, s4, v141, v39
	ds_write_b16_d16_hi v135, v40
	s_waitcnt lgkmcnt(2)
	v_fma_f32 v40, v123, v136, v127
	v_fmac_f32_e32 v40, v124, v137
	ds_read2st64_b32 v[136:137], v143 offset0:70 offset1:71
	v_add3_u32 v135, s25, v142, v2
	s_waitcnt lgkmcnt(0)
	v_fmac_f32_e32 v40, v125, v136
	v_fmac_f32_e32 v40, v126, v137
	ds_read2st64_b32 v[136:137], v156 offset0:68 offset1:69
	ds_write_b32 v135, v40
	v_bfe_u32 v135, v40, 16, 1
	v_add3_u32 v40, v40, v135, s97
	v_add3_u32 v135, s4, v154, v39
	ds_write_b16_d16_hi v135, v40
	s_waitcnt lgkmcnt(2)
	v_fma_f32 v40, v123, v136, v127
	v_fmac_f32_e32 v40, v124, v137
	ds_read2st64_b32 v[136:137], v156 offset0:70 offset1:71
	v_add3_u32 v135, s25, v155, v2
	s_waitcnt lgkmcnt(0)
	v_fmac_f32_e32 v40, v125, v136
	v_fmac_f32_e32 v40, v126, v137
	ds_read2st64_b32 v[136:137], v159 offset0:68 offset1:69
	ds_write_b32 v135, v40
	v_bfe_u32 v135, v40, 16, 1
	v_add3_u32 v40, v40, v135, s97
	v_add3_u32 v135, s4, v157, v39
	ds_write_b16_d16_hi v135, v40
	s_waitcnt lgkmcnt(2)
	v_fma_f32 v40, v123, v136, v127
	v_fmac_f32_e32 v40, v124, v137
	ds_read2st64_b32 v[136:137], v159 offset0:70 offset1:71
	v_add3_u32 v135, s25, v158, v2
	s_waitcnt lgkmcnt(0)
	v_fmac_f32_e32 v40, v125, v136
	v_fmac_f32_e32 v40, v126, v137
	ds_read2st64_b32 v[136:137], v162 offset0:68 offset1:69
	ds_write_b32 v135, v40
	v_bfe_u32 v135, v40, 16, 1
	v_add3_u32 v40, v40, v135, s97
	v_add3_u32 v135, s4, v160, v39
	ds_write_b16_d16_hi v135, v40
	s_waitcnt lgkmcnt(2)
	v_fma_f32 v40, v123, v136, v127
	v_fmac_f32_e32 v40, v124, v137
	ds_read2st64_b32 v[136:137], v162 offset0:70 offset1:71
	v_add3_u32 v135, s25, v161, v2
	s_waitcnt lgkmcnt(0)
	v_fmac_f32_e32 v40, v125, v136
	v_fmac_f32_e32 v40, v126, v137
	ds_read2st64_b32 v[136:137], v165 offset0:68 offset1:69
	ds_write_b32 v135, v40
	v_bfe_u32 v135, v40, 16, 1
	v_add3_u32 v40, v40, v135, s97
	v_add3_u32 v135, s4, v163, v39
	ds_write_b16_d16_hi v135, v40
	s_waitcnt lgkmcnt(2)
	v_fma_f32 v40, v123, v136, v127
	v_fmac_f32_e32 v40, v124, v137
	ds_read2st64_b32 v[136:137], v165 offset0:70 offset1:71
	v_add3_u32 v135, s25, v164, v2
	s_waitcnt lgkmcnt(0)
	v_fmac_f32_e32 v40, v125, v136
	v_fmac_f32_e32 v40, v126, v137
	ds_read2st64_b32 v[136:137], v167 offset0:68 offset1:69
	ds_write_b32 v135, v40
	v_bfe_u32 v135, v40, 16, 1
	v_add3_u32 v40, v40, v135, s97
	v_add3_u32 v135, s4, v166, v39
	ds_write_b16_d16_hi v135, v40
	s_waitcnt lgkmcnt(2)
	v_fma_f32 v40, v123, v136, v127
	v_fmac_f32_e32 v40, v124, v137
	ds_read2st64_b32 v[136:137], v167 offset0:70 offset1:71
	v_add3_u32 v135, s25, v138, v2
	v_add3_u32 v39, s4, v168, v39
	s_waitcnt lgkmcnt(0)
	v_fmac_f32_e32 v40, v125, v136
	v_fmac_f32_e32 v40, v126, v137
	ds_write_b32 v135, v40
	v_bfe_u32 v135, v40, 16, 1
	v_add3_u32 v40, v40, v135, s97
	ds_write_b16_d16_hi v39, v40
	v_and_b32_e32 v39, -16, v36
	v_lshlrev_b32_e32 v135, 2, v38
	v_mul_u32_u24_e32 v38, 0x90, v38
	v_add3_u32 v39, s65, v39, v38
	s_waitcnt lgkmcnt(0)
	s_barrier
	ds_read_b128 v[136:139], v39
	ds_read_b128 v[140:143], v39 offset:64
	s_waitcnt lgkmcnt(1)
	v_mfma_f32_16x16x32_bf16 v[136:139], v[136:139], v[20:23], 0
	v_lshrrev_b32_e32 v40, 2, v36
	v_and_b32_e32 v40, 0xfffffc, v40
	s_waitcnt lgkmcnt(0)
	v_mfma_f32_16x16x32_bf16 v[136:139], v[140:143], v[24:27], v[136:139]
	s_nop 7
	v_add_f32_e32 v38, v128, v136
	v_mul_f32_e32 v38, 0xbfb8aa3b, v38
	v_exp_f32_e32 v38, v38
	s_nop 0
	v_add_f32_e32 v38, 1.0, v38
	v_rcp_f32_e32 v136, v38
	v_add_lshl_u32 v38, v40, s60, 8
	v_add_f32_e32 v40, v128, v137
	v_mul_f32_e32 v40, 0xbfb8aa3b, v40
	v_exp_f32_e32 v40, v40
	v_add3_u32 v38, s13, v135, v38
	v_add_f32_e32 v135, v128, v139
	v_mul_f32_e32 v135, 0xbfb8aa3b, v135
	v_add_f32_e32 v40, 1.0, v40
	v_rcp_f32_e32 v40, v40
	v_exp_f32_e32 v135, v135
	ds_write2st64_b32 v38, v136, v40 offset1:1
	v_add_f32_e32 v40, v128, v138
	v_mul_f32_e32 v40, 0xbfb8aa3b, v40
	v_exp_f32_e32 v40, v40
	v_add_f32_e32 v135, 1.0, v135
	v_rcp_f32_e32 v135, v135
	v_add_f32_e32 v40, 1.0, v40
	v_rcp_f32_e32 v40, v40
	ds_write2st64_b32 v38, v40, v135 offset0:2 offset1:3
	ds_read_b128 v[136:139], v39 offset:2304
	ds_read_b128 v[140:143], v39 offset:2368
	s_waitcnt lgkmcnt(1)
	v_mfma_f32_16x16x32_bf16 v[136:139], v[136:139], v[20:23], 0
	s_waitcnt lgkmcnt(0)
	v_mfma_f32_16x16x32_bf16 v[136:139], v[140:143], v[24:27], v[136:139]
	s_nop 7
	v_add_f32_e32 v40, v128, v136
	v_add_f32_e32 v135, v128, v137
	v_mul_f32_e32 v40, 0xbfb8aa3b, v40
	v_mul_f32_e32 v135, 0xbfb8aa3b, v135
	v_exp_f32_e32 v40, v40
	v_exp_f32_e32 v135, v135
	v_add_f32_e32 v40, 1.0, v40
	v_add_f32_e32 v135, 1.0, v135
	v_rcp_f32_e32 v40, v40
	v_rcp_f32_e32 v135, v135
	ds_write2st64_b32 v38, v40, v135 offset0:16 offset1:17
	v_add_f32_e32 v40, v128, v138
	v_add_f32_e32 v135, v128, v139
	v_mul_f32_e32 v40, 0xbfb8aa3b, v40
	v_mul_f32_e32 v135, 0xbfb8aa3b, v135
	v_exp_f32_e32 v40, v40
	v_exp_f32_e32 v135, v135
	v_add_f32_e32 v40, 1.0, v40
	v_add_f32_e32 v135, 1.0, v135
	v_rcp_f32_e32 v40, v40
	v_rcp_f32_e32 v135, v135
	ds_write2st64_b32 v38, v40, v135 offset0:18 offset1:19
	ds_read_b128 v[136:139], v39 offset:4608
	ds_read_b128 v[140:143], v39 offset:4672
	s_waitcnt lgkmcnt(1)
	v_mfma_f32_16x16x32_bf16 v[136:139], v[136:139], v[20:23], 0
	s_waitcnt lgkmcnt(0)
	v_mfma_f32_16x16x32_bf16 v[136:139], v[140:143], v[24:27], v[136:139]
	s_nop 7
	v_add_f32_e32 v40, v128, v136
	v_add_f32_e32 v135, v128, v137
	v_mul_f32_e32 v40, 0xbfb8aa3b, v40
	v_mul_f32_e32 v135, 0xbfb8aa3b, v135
	v_exp_f32_e32 v40, v40
	v_exp_f32_e32 v135, v135
	v_add_f32_e32 v40, 1.0, v40
	v_add_f32_e32 v135, 1.0, v135
	v_rcp_f32_e32 v40, v40
	v_rcp_f32_e32 v135, v135
	ds_write2st64_b32 v38, v40, v135 offset0:32 offset1:33
	v_add_f32_e32 v40, v128, v138
	v_add_f32_e32 v135, v128, v139
	v_mul_f32_e32 v40, 0xbfb8aa3b, v40
	v_mul_f32_e32 v135, 0xbfb8aa3b, v135
	v_exp_f32_e32 v40, v40
	v_exp_f32_e32 v135, v135
	v_add_f32_e32 v40, 1.0, v40
	v_add_f32_e32 v135, 1.0, v135
	v_rcp_f32_e32 v40, v40
	v_rcp_f32_e32 v135, v135
	ds_write2st64_b32 v38, v40, v135 offset0:34 offset1:35
	ds_read_b128 v[136:139], v39 offset:6912
	ds_read_b128 v[140:143], v39 offset:6976
	s_waitcnt lgkmcnt(1)
	v_mfma_f32_16x16x32_bf16 v[136:139], v[136:139], v[20:23], 0
	s_waitcnt lgkmcnt(0)
	v_mfma_f32_16x16x32_bf16 v[136:139], v[140:143], v[24:27], v[136:139]
	s_nop 7
	v_add_f32_e32 v40, v128, v136
	v_add_f32_e32 v135, v128, v137
	v_mul_f32_e32 v40, 0xbfb8aa3b, v40
	v_mul_f32_e32 v135, 0xbfb8aa3b, v135
	v_exp_f32_e32 v40, v40
	v_exp_f32_e32 v135, v135
	v_add_f32_e32 v40, 1.0, v40
	v_add_f32_e32 v135, 1.0, v135
	v_rcp_f32_e32 v40, v40
	v_rcp_f32_e32 v135, v135
	ds_write2st64_b32 v38, v40, v135 offset0:48 offset1:49
	v_add_f32_e32 v40, v128, v138
	v_add_f32_e32 v135, v128, v139
	v_mul_f32_e32 v40, 0xbfb8aa3b, v40
	v_mul_f32_e32 v135, 0xbfb8aa3b, v135
	v_exp_f32_e32 v40, v40
	v_exp_f32_e32 v135, v135
	v_add_f32_e32 v40, 1.0, v40
	v_add_f32_e32 v135, 1.0, v135
	v_rcp_f32_e32 v40, v40
	v_rcp_f32_e32 v135, v135
	ds_write2st64_b32 v38, v40, v135 offset0:50 offset1:51
	ds_read_b128 v[136:139], v39 offset:9216
	ds_read_b128 v[140:143], v39 offset:9280
	s_waitcnt lgkmcnt(1)
	v_mfma_f32_16x16x32_bf16 v[136:139], v[136:139], v[28:31], 0
	s_waitcnt lgkmcnt(0)
	v_mfma_f32_16x16x32_bf16 v[136:139], v[140:143], v[32:35], v[136:139]
	s_waitcnt vmcnt(0)
	s_nop 6
	v_add_f32_e32 v40, v129, v136
	v_add_f32_e32 v135, v129, v137
	v_mul_f32_e32 v40, 0xbfb8aa3b, v40
	v_mul_f32_e32 v135, 0xbfb8aa3b, v135
	v_exp_f32_e32 v40, v40
	v_exp_f32_e32 v135, v135
	v_add_f32_e32 v40, 1.0, v40
	v_add_f32_e32 v135, 1.0, v135
	v_rcp_f32_e32 v40, v40
	v_rcp_f32_e32 v135, v135
	ds_write2st64_b32 v38, v40, v135 offset0:128 offset1:129
	v_add_f32_e32 v40, v129, v138
	v_add_f32_e32 v135, v129, v139
	v_mul_f32_e32 v40, 0xbfb8aa3b, v40
	v_mul_f32_e32 v135, 0xbfb8aa3b, v135
	v_exp_f32_e32 v40, v40
	v_exp_f32_e32 v135, v135
	v_add_f32_e32 v40, 1.0, v40
	v_add_f32_e32 v135, 1.0, v135
	v_rcp_f32_e32 v40, v40
	v_rcp_f32_e32 v135, v135
	ds_write2st64_b32 v38, v40, v135 offset0:130 offset1:131
	ds_read_b128 v[136:139], v39 offset:11520
	ds_read_b128 v[140:143], v39 offset:11584
	s_waitcnt lgkmcnt(1)
	v_mfma_f32_16x16x32_bf16 v[136:139], v[136:139], v[28:31], 0
	s_waitcnt lgkmcnt(0)
	v_mfma_f32_16x16x32_bf16 v[136:139], v[140:143], v[32:35], v[136:139]
	s_nop 7
	v_add_f32_e32 v40, v129, v136
	v_add_f32_e32 v135, v129, v137
	v_mul_f32_e32 v40, 0xbfb8aa3b, v40
	v_mul_f32_e32 v135, 0xbfb8aa3b, v135
	v_exp_f32_e32 v40, v40
	v_exp_f32_e32 v135, v135
	v_add_f32_e32 v40, 1.0, v40
	v_add_f32_e32 v135, 1.0, v135
	v_rcp_f32_e32 v40, v40
	v_rcp_f32_e32 v135, v135
	ds_write2st64_b32 v38, v40, v135 offset0:144 offset1:145
	v_add_f32_e32 v40, v129, v138
	v_add_f32_e32 v135, v129, v139
	v_mul_f32_e32 v40, 0xbfb8aa3b, v40
	v_mul_f32_e32 v135, 0xbfb8aa3b, v135
	v_exp_f32_e32 v40, v40
	v_exp_f32_e32 v135, v135
	v_add_f32_e32 v40, 1.0, v40
	v_add_f32_e32 v135, 1.0, v135
	v_rcp_f32_e32 v40, v40
	v_rcp_f32_e32 v135, v135
	ds_write2st64_b32 v38, v40, v135 offset0:146 offset1:147
	ds_read_b128 v[136:139], v39 offset:13824
	ds_read_b128 v[140:143], v39 offset:13888
	s_waitcnt lgkmcnt(1)
	v_mfma_f32_16x16x32_bf16 v[136:139], v[136:139], v[28:31], 0
	s_waitcnt lgkmcnt(0)
	v_mfma_f32_16x16x32_bf16 v[136:139], v[140:143], v[32:35], v[136:139]
	s_nop 7
	v_add_f32_e32 v40, v129, v136
	v_add_f32_e32 v135, v129, v137
	v_mul_f32_e32 v40, 0xbfb8aa3b, v40
	v_mul_f32_e32 v135, 0xbfb8aa3b, v135
	v_exp_f32_e32 v40, v40
	v_exp_f32_e32 v135, v135
	v_add_f32_e32 v40, 1.0, v40
	v_add_f32_e32 v135, 1.0, v135
	v_rcp_f32_e32 v40, v40
	v_rcp_f32_e32 v135, v135
	ds_write2st64_b32 v38, v40, v135 offset0:160 offset1:161
	v_add_f32_e32 v40, v129, v138
	v_add_f32_e32 v135, v129, v139
	v_mul_f32_e32 v40, 0xbfb8aa3b, v40
	v_mul_f32_e32 v135, 0xbfb8aa3b, v135
	v_exp_f32_e32 v40, v40
	v_exp_f32_e32 v135, v135
	v_add_f32_e32 v40, 1.0, v40
	v_add_f32_e32 v135, 1.0, v135
	v_rcp_f32_e32 v40, v40
	v_rcp_f32_e32 v135, v135
	ds_write2st64_b32 v38, v40, v135 offset0:162 offset1:163
	ds_read_b128 v[136:139], v39 offset:16128
	ds_read_b128 v[140:143], v39 offset:16192
	s_waitcnt lgkmcnt(1)
	v_mfma_f32_16x16x32_bf16 v[136:139], v[136:139], v[28:31], 0
	s_waitcnt lgkmcnt(0)
	v_mfma_f32_16x16x32_bf16 v[136:139], v[140:143], v[32:35], v[136:139]
	s_nop 7
	v_add_f32_e32 v39, v129, v136
	v_add_f32_e32 v40, v129, v137
	v_mul_f32_e32 v39, 0xbfb8aa3b, v39
	v_mul_f32_e32 v40, 0xbfb8aa3b, v40
	v_exp_f32_e32 v39, v39
	v_exp_f32_e32 v40, v40
	v_add_f32_e32 v39, 1.0, v39
	v_add_f32_e32 v40, 1.0, v40
	v_rcp_f32_e32 v39, v39
	v_rcp_f32_e32 v40, v40
	ds_write2st64_b32 v38, v39, v40 offset0:176 offset1:177
	v_add_f32_e32 v39, v129, v138
	v_add_f32_e32 v40, v129, v139
	v_mul_f32_e32 v39, 0xbfb8aa3b, v39
	v_mul_f32_e32 v40, 0xbfb8aa3b, v40
	v_exp_f32_e32 v39, v39
	v_exp_f32_e32 v40, v40
	v_add_f32_e32 v39, 1.0, v39
	v_add_f32_e32 v40, 1.0, v40
	v_rcp_f32_e32 v39, v39
	v_rcp_f32_e32 v40, v40
	ds_write2st64_b32 v38, v39, v40 offset0:178 offset1:179
	s_waitcnt lgkmcnt(0)
	s_barrier
	ds_read_b32 v38, v0
	ds_read_b32 v39, v0 offset:16384
	ds_read_b32 v40, v3
	s_waitcnt lgkmcnt(2)
	v_mul_f32_e32 v38, v130, v38
	v_mul_f32_e32 v38, 0x3fb8aa3b, v38
	v_exp_f32_e32 v38, v38
	s_waitcnt lgkmcnt(0)
	v_mul_f32_e32 v39, v39, v40
	v_fma_f32 v135, -v38, v38, 1.0
	v_max_f32_e32 v135, 0, v135
	v_sqrt_f32_e32 v135, v135
	s_nop 0
	v_mul_f32_e32 v39, v39, v135
	ds_write_b32 v0, v38
	ds_write_b32 v0, v39 offset:16384
	v_lshlrev_b32_e32 v38, 2, v134
	v_and_b32_e32 v40, 0xffffff00, v38
	v_add3_u32 v135, 0, v40, v2
	ds_read2st64_b32 v[38:39], v135 offset1:64
	v_add3_u32 v136, s24, v40, v2
	ds_read_b32 v136, v136
	v_add3_u32 v2, s25, v40, v2
	s_waitcnt lgkmcnt(1)
	v_mul_f32_e32 v38, v130, v38
	v_mul_f32_e32 v38, 0x3fb8aa3b, v38
	v_exp_f32_e32 v38, v38
	s_waitcnt lgkmcnt(0)
	v_mul_f32_e32 v39, v39, v136
	v_fma_f32 v137, -v38, v38, 1.0
	v_max_f32_e32 v137, 0, v137
	v_sqrt_f32_e32 v137, v137
	s_nop 0
	v_mul_f32_e32 v39, v39, v137
	ds_write2st64_b32 v135, v38, v39 offset1:64
	ds_read2st64_b32 v[38:39], v0 offset0:16 offset1:24
	ds_read2st64_b32 v[136:137], v0 offset0:80 offset1:88
	ds_read2st64_b32 v[138:139], v3 offset0:16 offset1:24
	s_waitcnt lgkmcnt(2)
	v_mul_f32_e32 v38, v130, v38
	v_mul_f32_e32 v39, v130, v39
	v_mul_f32_e32 v38, 0x3fb8aa3b, v38
	v_mul_f32_e32 v39, 0x3fb8aa3b, v39
	v_exp_f32_e32 v38, v38
	v_exp_f32_e32 v39, v39
	s_waitcnt lgkmcnt(0)
	v_mul_f32_e32 v136, v136, v138
	v_mul_f32_e32 v137, v137, v139
	v_fma_f32 v140, -v38, v38, 1.0
	v_fma_f32 v138, -v39, v39, 1.0
	v_max_f32_e32 v140, 0, v140
	v_max_f32_e32 v138, 0, v138
	v_sqrt_f32_e32 v140, v140
	v_sqrt_f32_e32 v138, v138
	v_mul_f32_e32 v136, v136, v140
	v_mul_f32_e32 v137, v137, v138
	ds_write2st64_b32 v0, v38, v39 offset0:16 offset1:24
	ds_write2st64_b32 v0, v136, v137 offset0:80 offset1:88
	ds_read2st64_b32 v[38:39], v0 offset0:32 offset1:40
	ds_read2st64_b32 v[136:137], v0 offset0:96 offset1:104
	ds_read2st64_b32 v[138:139], v3 offset0:32 offset1:40
	s_waitcnt lgkmcnt(2)
	v_mul_f32_e32 v38, v130, v38
	v_mul_f32_e32 v39, v130, v39
	v_mul_f32_e32 v38, 0x3fb8aa3b, v38
	v_mul_f32_e32 v39, 0x3fb8aa3b, v39
	v_exp_f32_e32 v38, v38
	v_exp_f32_e32 v39, v39
	s_waitcnt lgkmcnt(0)
	v_mul_f32_e32 v136, v136, v138
	v_mul_f32_e32 v137, v137, v139
	v_fma_f32 v140, -v38, v38, 1.0
	v_fma_f32 v138, -v39, v39, 1.0
	v_max_f32_e32 v140, 0, v140
	v_max_f32_e32 v138, 0, v138
	v_sqrt_f32_e32 v140, v140
	v_sqrt_f32_e32 v138, v138
	v_mul_f32_e32 v136, v136, v140
	v_mul_f32_e32 v137, v137, v138
	ds_write2st64_b32 v0, v38, v39 offset0:32 offset1:40
	ds_write2st64_b32 v0, v136, v137 offset0:96 offset1:104
	ds_read2st64_b32 v[38:39], v0 offset0:48 offset1:56
	ds_read2st64_b32 v[136:137], v0 offset0:112 offset1:120
	ds_read2st64_b32 v[138:139], v3 offset0:48 offset1:56
	s_waitcnt lgkmcnt(2)
	v_mul_f32_e32 v3, v130, v38
	v_mul_f32_e32 v3, 0x3fb8aa3b, v3
	v_exp_f32_e32 v3, v3
	v_mul_f32_e32 v39, v130, v39
	v_mul_f32_e32 v39, 0x3fb8aa3b, v39
	v_exp_f32_e32 v39, v39
	v_fma_f32 v38, -v3, v3, 1.0
	v_max_f32_e32 v38, 0, v38
	v_sqrt_f32_e32 v38, v38
	s_waitcnt lgkmcnt(0)
	v_mul_f32_e32 v136, v136, v138
	v_mul_f32_e32 v137, v137, v139
	v_mul_f32_e32 v38, v136, v38
	v_fma_f32 v136, -v39, v39, 1.0
	v_max_f32_e32 v136, 0, v136
	v_sqrt_f32_e32 v136, v136
	s_nop 0
	v_mul_f32_e32 v136, v137, v136
	ds_write2st64_b32 v0, v3, v39 offset0:48 offset1:56
	ds_write2st64_b32 v0, v38, v136 offset0:112 offset1:120
	ds_read_b32 v3, v0 offset:32768
	ds_read_b32 v38, v0 offset:49152
	ds_read_b32 v39, v37
	s_waitcnt lgkmcnt(2)
	v_mul_f32_e32 v3, v131, v3
	v_mul_f32_e32 v3, 0x3fb8aa3b, v3
	v_exp_f32_e32 v3, v3
	s_waitcnt lgkmcnt(0)
	v_mul_f32_e32 v38, v38, v39
	v_fma_f32 v136, -v3, v3, 1.0
	v_max_f32_e32 v136, 0, v136
	v_sqrt_f32_e32 v136, v136
	s_nop 0
	v_mul_f32_e32 v38, v38, v136
	ds_write_b32 v0, v3 offset:32768
	ds_write_b32 v0, v38 offset:49152
	ds_read2st64_b32 v[38:39], v135 offset0:128 offset1:192
	ds_read_b32 v2, v2
	s_waitcnt lgkmcnt(1)
	v_mul_f32_e32 v3, v131, v38
	v_mul_f32_e32 v3, 0x3fb8aa3b, v3
	v_exp_f32_e32 v3, v3
	s_waitcnt lgkmcnt(0)
	v_mul_f32_e32 v2, v39, v2
	v_fma_f32 v38, -v3, v3, 1.0
	v_max_f32_e32 v38, 0, v38
	v_sqrt_f32_e32 v38, v38
	s_nop 0
	v_mul_f32_e32 v2, v2, v38
	ds_write2st64_b32 v135, v3, v2 offset0:128 offset1:192
	ds_read2st64_b32 v[2:3], v0 offset0:144 offset1:152
	ds_read2st64_b32 v[38:39], v0 offset0:208 offset1:216
	ds_read2st64_b32 v[136:137], v37 offset0:16 offset1:24
	s_waitcnt lgkmcnt(2)
	v_mul_f32_e32 v2, v131, v2
	v_mul_f32_e32 v2, 0x3fb8aa3b, v2
	v_exp_f32_e32 v2, v2
	v_mul_f32_e32 v3, v131, v3
	v_mul_f32_e32 v3, 0x3fb8aa3b, v3
	v_exp_f32_e32 v3, v3
	v_fma_f32 v40, -v2, v2, 1.0
	v_max_f32_e32 v40, 0, v40
	v_sqrt_f32_e32 v40, v40
	s_waitcnt lgkmcnt(0)
	v_mul_f32_e32 v38, v38, v136
	v_mul_f32_e32 v39, v39, v137
	v_mul_f32_e32 v38, v38, v40
	v_fma_f32 v40, -v3, v3, 1.0
	v_max_f32_e32 v40, 0, v40
	v_sqrt_f32_e32 v40, v40
	s_nop 0
	v_mul_f32_e32 v39, v39, v40
	ds_write2st64_b32 v0, v2, v3 offset0:144 offset1:152
	ds_write2st64_b32 v0, v38, v39 offset0:208 offset1:216
	ds_read2st64_b32 v[2:3], v0 offset0:160 offset1:168
	ds_read2st64_b32 v[38:39], v0 offset0:224 offset1:232
	ds_read2st64_b32 v[136:137], v37 offset0:32 offset1:40
	s_waitcnt lgkmcnt(2)
	v_mul_f32_e32 v2, v131, v2
	v_mul_f32_e32 v2, 0x3fb8aa3b, v2
	v_exp_f32_e32 v2, v2
	v_mul_f32_e32 v3, v131, v3
	v_mul_f32_e32 v3, 0x3fb8aa3b, v3
	v_exp_f32_e32 v3, v3
	v_fma_f32 v40, -v2, v2, 1.0
	v_max_f32_e32 v40, 0, v40
	v_sqrt_f32_e32 v40, v40
	s_waitcnt lgkmcnt(0)
	v_mul_f32_e32 v38, v38, v136
	v_mul_f32_e32 v39, v39, v137
	v_mul_f32_e32 v38, v38, v40
	v_fma_f32 v40, -v3, v3, 1.0
	v_max_f32_e32 v40, 0, v40
	v_sqrt_f32_e32 v40, v40
	s_nop 0
	v_mul_f32_e32 v39, v39, v40
	ds_write2st64_b32 v0, v2, v3 offset0:160 offset1:168
	ds_write2st64_b32 v0, v38, v39 offset0:224 offset1:232
	ds_read2st64_b32 v[2:3], v0 offset0:176 offset1:184
	ds_read2st64_b32 v[38:39], v0 offset0:240 offset1:248
	ds_read2st64_b32 v[136:137], v37 offset0:48 offset1:56
	s_waitcnt lgkmcnt(2)
	v_mul_f32_e32 v2, v131, v2
	v_mul_f32_e32 v2, 0x3fb8aa3b, v2
	v_exp_f32_e32 v2, v2
	v_mul_f32_e32 v3, v131, v3
	v_mul_f32_e32 v3, 0x3fb8aa3b, v3
	v_exp_f32_e32 v3, v3
	v_fma_f32 v37, -v2, v2, 1.0
	v_max_f32_e32 v37, 0, v37
	v_sqrt_f32_e32 v37, v37
	s_waitcnt lgkmcnt(0)
	v_mul_f32_e32 v38, v38, v136
	v_mul_f32_e32 v39, v39, v137
	v_mul_f32_e32 v37, v38, v37
	v_fma_f32 v38, -v3, v3, 1.0
	v_max_f32_e32 v38, 0, v38
	v_sqrt_f32_e32 v38, v38
	s_nop 0
	v_mul_f32_e32 v38, v39, v38
	ds_write2st64_b32 v0, v2, v3 offset0:176 offset1:184
	ds_write2st64_b32 v0, v37, v38 offset0:240 offset1:248
	s_waitcnt lgkmcnt(0)
	s_barrier
	s_cbranch_vccnz .LBB0_286
	v_lshlrev_b32_e32 v2, 2, v36
	v_add_u32_e32 v0, s61, v2
	s_sub_u32 s35, s64, s61
	s_mov_b32 s25, 0
	s_mov_b32 s26, 56
.Llru_rec:
	s_and_b64 s[36:37], s[48:49], exec
	s_cselect_b32 s27, s25, s26
	s_lshl_b32 s27, s27, 8
	v_add_u32_e32 v3, s27, v0
	ds_read2st64_b32 v[154:155], v3 offset1:64
	ds_read2st64_b32 v[156:157], v3 offset0:1 offset1:65
	ds_read2st64_b32 v[158:159], v3 offset0:2 offset1:66
	ds_read2st64_b32 v[160:161], v3 offset0:3 offset1:67
	ds_read2st64_b32 v[162:163], v3 offset0:4 offset1:68
	ds_read2st64_b32 v[164:165], v3 offset0:5 offset1:69
	ds_read2st64_b32 v[166:167], v3 offset0:6 offset1:70
	ds_read2st64_b32 v[168:169], v3 offset0:7 offset1:71
	v_add_u32_e32 v40, s35, v3
	s_and_b64 s[36:37], s[48:49], exec
	s_cbranch_scc0 .Llru_rec_bwd
	s_waitcnt lgkmcnt(0)
	v_fmac_f32_e32 v155, v41, v154
	v_fmac_f32_e32 v157, v155, v156
	v_fmac_f32_e32 v159, v157, v158
	v_fmac_f32_e32 v161, v159, v160
	v_fmac_f32_e32 v163, v161, v162
	v_fmac_f32_e32 v165, v163, v164
	v_fmac_f32_e32 v167, v165, v166
	v_fmac_f32_e32 v169, v167, v168
	v_mov_b32_e32 v41, v169
	s_branch .Llru_rec_wr
.Llru_rec_bwd:
	s_waitcnt lgkmcnt(0)
	v_fmac_f32_e32 v169, v41, v168
	v_fmac_f32_e32 v167, v169, v166
	v_fmac_f32_e32 v165, v167, v164
	v_fmac_f32_e32 v163, v165, v162
	v_fmac_f32_e32 v161, v163, v160
	v_fmac_f32_e32 v159, v161, v158
	v_fmac_f32_e32 v157, v159, v156
	v_fmac_f32_e32 v155, v157, v154
	v_mov_b32_e32 v41, v155
.Llru_rec_wr:
	ds_write_b32 v40, v155
	ds_write_b32 v40, v157 offset:256
	ds_write_b32 v40, v159 offset:512
	ds_write_b32 v40, v161 offset:768
	ds_write_b32 v40, v163 offset:1024
	ds_write_b32 v40, v165 offset:1280
	ds_write_b32 v40, v167 offset:1536
	ds_write_b32 v40, v169 offset:1792
	s_add_i32 s26, s26, -8
	s_add_i32 s25, s25, 8
	s_cmp_lg_u32 s25, 64
	s_cbranch_scc1 .Llru_rec

.LBB0_297:
	s_and_b64 vcc, exec, s[24:25]
	s_cbranch_vccz .LBB0_239
	v_mbcnt_lo_u32_b32 v0, -1, 0
	v_mbcnt_hi_u32_b32 v0, -1, v0
	v_readlane_b32 s34, v254, 30
	s_lshr_b32 s26, s12, 1
	s_and_b32 s52, s12, 1
	s_mul_hi_u32 s53, s26, 0xaaaaaaab
	s_lshr_b32 s53, s53, 3
	s_mul_i32 s27, s53, 12
	s_sub_u32 s27, s26, s27
	s_lshr_b32 s24, s27, 1
	s_and_b32 s35, s27, 1
	s_add_i32 s26, s38, -1
	s_lshr_b32 s26, s26, 4
	s_and_b32 s36, s26, 1
	s_cmp_eq_u32 s35, 0
	s_cselect_b32 s37, 1, -1
	s_lshl_b32 s44, s53, 8
	s_add_u32 s44, s44, 0x8000
	s_lshl_b32 s45, s53, 12
	s_mov_b32 s2, 0
	s_cmp_gt_u32 s34, 3
	s_cbranch_scc1 .Lrc_setup_stage
	s_setprio 3
	v_and_b32_e32 v176, 15, v0
	v_lshrrev_b32_e32 v177, 4, v0
	v_lshlrev_b32_e32 v177, 1, v177
	v_lshl_add_u32 v178, s34, 3, v177
	v_lshlrev_b32_e32 v42, 4, v176
	v_lshl_add_u32 v179, s52, 5, v178
	v_lshlrev_b32_e32 v43, 2, v179
	v_add_u32_e32 v43, 0x500, v43
	v_mul_u32_u24_e32 v44, 144, v176
	v_lshl_add_u32 v44, v178, 2, v44
	v_add_u32_e32 v44, 0x18000, v44
	v_and_b32_e32 v179, 8, v176
	v_cmp_ne_u32_e64 s[56:57], 0, v179
	v_and_b32_e32 v179, 4, v176
	v_cmp_ne_u32_e64 s[82:83], 0, v179
	v_and_b32_e32 v179, 2, v176
	v_cmp_ne_u32_e64 s[84:85], 0, v179
	v_and_b32_e32 v179, 1, v176
	v_cmp_ne_u32_e64 s[88:89], 0, v179
	v_mov_b32_e32 v2, 0
	v_mov_b32_e32 v3, 0
	v_mov_b32_e32 v4, 0
	v_mov_b32_e32 v5, 0
	v_mov_b32_e32 v6, 0
	v_mov_b32_e32 v7, 0
	v_mov_b32_e32 v8, 0
	v_mov_b32_e32 v9, 0
	s_branch .Lrc_setup_done

.Lrc_chunk:
	s_cmp_gt_u32 s34, 3
	s_cbranch_scc1 .Lrc_stage
	ds_read_b128 v[134:137], v42 offset:768
	ds_read_b128 v[130:133], v42 offset:512
	ds_read_b64 v[142:143], v43 offset:0
	ds_read_b128 v[122:125], v42 offset:0
	ds_read_b128 v[126:129], v42 offset:256
	ds_read_b128 v[138:141], v42 offset:1024
	s_waitcnt lgkmcnt(0)
	ds_read_b128 v[166:169], v42 offset:2304
	ds_read_b128 v[162:165], v42 offset:2048
	ds_read_b64 v[174:175], v43 offset:1536
	ds_read_b128 v[154:157], v42 offset:1536
	ds_read_b128 v[158:161], v42 offset:1792
	ds_read_b128 v[170:173], v42 offset:2560
	v_pk_mul_f32 v[176:177], v[2:3], v[134:135]
	v_pk_mul_f32 v[178:179], v[6:7], v[134:135]
	v_pk_fma_f32 v[176:177], v[4:5], v[136:137], v[176:177]
	v_pk_fma_f32 v[178:179], v[8:9], v[136:137], v[178:179]
	v_pk_mul_f32 v[180:181], v[130:131], v[142:143] op_sel_hi:[1,0]
	v_add_f32_e32 v198, v176, v177
	v_pk_mul_f32 v[190:191], v[130:131], v[142:143] op_sel:[0,1] op_sel_hi:[1,1]
	v_add_f32_e32 v200, v178, v179
	v_pk_mul_f32 v[188:189], v[132:133], v[142:143] op_sel_hi:[1,0]
	v_add_f32_dpp v198, v198, v198 quad_perm:[1,0,3,2] row_mask:0xf bank_mask:0xf bound_ctrl:1
	v_pk_mul_f32 v[192:193], v[132:133], v[142:143] op_sel:[0,1] op_sel_hi:[1,1]
	v_add_f32_dpp v200, v200, v200 quad_perm:[1,0,3,2] row_mask:0xf bank_mask:0xf bound_ctrl:1
	v_pk_fma_f32 v[2:3], v[2:3], v[122:123], v[180:181]
	v_add_f32_dpp v198, v198, v198 quad_perm:[2,3,0,1] row_mask:0xf bank_mask:0xf bound_ctrl:1
	v_pk_fma_f32 v[6:7], v[6:7], v[122:123], v[190:191]
	v_add_f32_dpp v200, v200, v200 quad_perm:[2,3,0,1] row_mask:0xf bank_mask:0xf bound_ctrl:1
	v_pk_fma_f32 v[4:5], v[4:5], v[124:125], v[188:189]
	v_add_f32_dpp v198, v198, v198 row_half_mirror row_mask:0xf bank_mask:0xf bound_ctrl:1
	v_pk_fma_f32 v[8:9], v[8:9], v[124:125], v[192:193]
	v_add_f32_dpp v200, v200, v200 row_half_mirror row_mask:0xf bank_mask:0xf bound_ctrl:1
	s_nop 0
	v_add_f32_dpp v198, v198, v198 row_mirror row_mask:0xf bank_mask:0xf bound_ctrl:1
	s_nop 0
	v_add_f32_dpp v200, v200, v200 row_mirror row_mask:0xf bank_mask:0xf bound_ctrl:1
	v_pk_fma_f32 v[2:3], v[126:127], v[198:199], v[2:3] op_sel_hi:[1,0,1] neg_lo:[0,1,0] neg_hi:[0,1,0]
	v_pk_fma_f32 v[4:5], v[128:129], v[198:199], v[4:5] op_sel_hi:[1,0,1] neg_lo:[0,1,0] neg_hi:[0,1,0]
	v_pk_fma_f32 v[6:7], v[126:127], v[200:201], v[6:7] op_sel_hi:[1,0,1] neg_lo:[0,1,0] neg_hi:[0,1,0]
	v_pk_fma_f32 v[8:9], v[128:129], v[200:201], v[8:9] op_sel_hi:[1,0,1] neg_lo:[0,1,0] neg_hi:[0,1,0]
	v_pk_mul_f32 v[194:195], v[140:141], v[4:5]
	v_pk_mul_f32 v[196:197], v[140:141], v[8:9]
	v_pk_fma_f32 v[194:195], v[138:139], v[2:3], v[194:195]
	v_pk_fma_f32 v[196:197], v[138:139], v[6:7], v[196:197]
	v_add_f32_e32 v10, v194, v195
	v_add_f32_e32 v26, v196, v197
	s_waitcnt lgkmcnt(0)
	ds_read_b128 v[134:137], v42 offset:3840
	ds_read_b128 v[130:133], v42 offset:3584
	ds_read_b64 v[142:143], v43 offset:3072
	ds_read_b128 v[122:125], v42 offset:3072
	ds_read_b128 v[126:129], v42 offset:3328
	ds_read_b128 v[138:141], v42 offset:4096
	v_pk_mul_f32 v[176:177], v[2:3], v[166:167]
	v_pk_mul_f32 v[178:179], v[6:7], v[166:167]
	v_pk_fma_f32 v[176:177], v[4:5], v[168:169], v[176:177]
	v_pk_fma_f32 v[178:179], v[8:9], v[168:169], v[178:179]
	v_pk_mul_f32 v[180:181], v[162:163], v[174:175] op_sel_hi:[1,0]
	v_add_f32_e32 v198, v176, v177
	v_pk_mul_f32 v[190:191], v[162:163], v[174:175] op_sel:[0,1] op_sel_hi:[1,1]
	v_add_f32_e32 v200, v178, v179
	v_pk_mul_f32 v[188:189], v[164:165], v[174:175] op_sel_hi:[1,0]
	v_add_f32_dpp v198, v198, v198 quad_perm:[1,0,3,2] row_mask:0xf bank_mask:0xf bound_ctrl:1
	v_pk_mul_f32 v[192:193], v[164:165], v[174:175] op_sel:[0,1] op_sel_hi:[1,1]
	v_add_f32_dpp v200, v200, v200 quad_perm:[1,0,3,2] row_mask:0xf bank_mask:0xf bound_ctrl:1
	v_pk_fma_f32 v[2:3], v[2:3], v[154:155], v[180:181]
	v_add_f32_dpp v198, v198, v198 quad_perm:[2,3,0,1] row_mask:0xf bank_mask:0xf bound_ctrl:1
	v_pk_fma_f32 v[6:7], v[6:7], v[154:155], v[190:191]
	v_add_f32_dpp v200, v200, v200 quad_perm:[2,3,0,1] row_mask:0xf bank_mask:0xf bound_ctrl:1
	v_pk_fma_f32 v[4:5], v[4:5], v[156:157], v[188:189]
	v_add_f32_dpp v198, v198, v198 row_half_mirror row_mask:0xf bank_mask:0xf bound_ctrl:1
	v_pk_fma_f32 v[8:9], v[8:9], v[156:157], v[192:193]
	v_add_f32_dpp v200, v200, v200 row_half_mirror row_mask:0xf bank_mask:0xf bound_ctrl:1
	s_nop 0
	v_add_f32_dpp v198, v198, v198 row_mirror row_mask:0xf bank_mask:0xf bound_ctrl:1
	s_nop 0
	v_add_f32_dpp v200, v200, v200 row_mirror row_mask:0xf bank_mask:0xf bound_ctrl:1
	v_pk_fma_f32 v[2:3], v[158:159], v[198:199], v[2:3] op_sel_hi:[1,0,1] neg_lo:[0,1,0] neg_hi:[0,1,0]
	v_pk_fma_f32 v[4:5], v[160:161], v[198:199], v[4:5] op_sel_hi:[1,0,1] neg_lo:[0,1,0] neg_hi:[0,1,0]
	v_pk_fma_f32 v[6:7], v[158:159], v[200:201], v[6:7] op_sel_hi:[1,0,1] neg_lo:[0,1,0] neg_hi:[0,1,0]
	v_pk_fma_f32 v[8:9], v[160:161], v[200:201], v[8:9] op_sel_hi:[1,0,1] neg_lo:[0,1,0] neg_hi:[0,1,0]
	v_pk_mul_f32 v[194:195], v[172:173], v[4:5]
	v_pk_mul_f32 v[196:197], v[172:173], v[8:9]
	v_pk_fma_f32 v[194:195], v[170:171], v[2:3], v[194:195]
	v_pk_fma_f32 v[196:197], v[170:171], v[6:7], v[196:197]
	v_add_f32_e32 v11, v194, v195
	v_add_f32_e32 v27, v196, v197
	s_waitcnt lgkmcnt(0)
	ds_read_b128 v[166:169], v42 offset:5376
	ds_read_b128 v[162:165], v42 offset:5120
	ds_read_b64 v[174:175], v43 offset:4608
	ds_read_b128 v[154:157], v42 offset:4608
	ds_read_b128 v[158:161], v42 offset:4864
	ds_read_b128 v[170:173], v42 offset:5632
	v_pk_mul_f32 v[176:177], v[2:3], v[134:135]
	v_pk_mul_f32 v[178:179], v[6:7], v[134:135]
	v_pk_fma_f32 v[176:177], v[4:5], v[136:137], v[176:177]
	v_pk_fma_f32 v[178:179], v[8:9], v[136:137], v[178:179]
	v_pk_mul_f32 v[180:181], v[130:131], v[142:143] op_sel_hi:[1,0]
	v_add_f32_e32 v198, v176, v177
	v_pk_mul_f32 v[190:191], v[130:131], v[142:143] op_sel:[0,1] op_sel_hi:[1,1]
	v_add_f32_e32 v200, v178, v179
	v_pk_mul_f32 v[188:189], v[132:133], v[142:143] op_sel_hi:[1,0]
	v_add_f32_dpp v198, v198, v198 quad_perm:[1,0,3,2] row_mask:0xf bank_mask:0xf bound_ctrl:1
	v_pk_mul_f32 v[192:193], v[132:133], v[142:143] op_sel:[0,1] op_sel_hi:[1,1]
	v_add_f32_dpp v200, v200, v200 quad_perm:[1,0,3,2] row_mask:0xf bank_mask:0xf bound_ctrl:1
	v_pk_fma_f32 v[2:3], v[2:3], v[122:123], v[180:181]
	v_add_f32_dpp v198, v198, v198 quad_perm:[2,3,0,1] row_mask:0xf bank_mask:0xf bound_ctrl:1
	v_pk_fma_f32 v[6:7], v[6:7], v[122:123], v[190:191]
	v_add_f32_dpp v200, v200, v200 quad_perm:[2,3,0,1] row_mask:0xf bank_mask:0xf bound_ctrl:1
	v_pk_fma_f32 v[4:5], v[4:5], v[124:125], v[188:189]
	v_add_f32_dpp v198, v198, v198 row_half_mirror row_mask:0xf bank_mask:0xf bound_ctrl:1
	v_pk_fma_f32 v[8:9], v[8:9], v[124:125], v[192:193]
	v_add_f32_dpp v200, v200, v200 row_half_mirror row_mask:0xf bank_mask:0xf bound_ctrl:1
	s_nop 0
	v_add_f32_dpp v198, v198, v198 row_mirror row_mask:0xf bank_mask:0xf bound_ctrl:1
	s_nop 0
	v_add_f32_dpp v200, v200, v200 row_mirror row_mask:0xf bank_mask:0xf bound_ctrl:1
	v_pk_fma_f32 v[2:3], v[126:127], v[198:199], v[2:3] op_sel_hi:[1,0,1] neg_lo:[0,1,0] neg_hi:[0,1,0]
	v_pk_fma_f32 v[4:5], v[128:129], v[198:199], v[4:5] op_sel_hi:[1,0,1] neg_lo:[0,1,0] neg_hi:[0,1,0]
	v_pk_fma_f32 v[6:7], v[126:127], v[200:201], v[6:7] op_sel_hi:[1,0,1] neg_lo:[0,1,0] neg_hi:[0,1,0]
	v_pk_fma_f32 v[8:9], v[128:129], v[200:201], v[8:9] op_sel_hi:[1,0,1] neg_lo:[0,1,0] neg_hi:[0,1,0]
	v_pk_mul_f32 v[194:195], v[140:141], v[4:5]
	v_pk_mul_f32 v[196:197], v[140:141], v[8:9]
	v_pk_fma_f32 v[194:195], v[138:139], v[2:3], v[194:195]
	v_pk_fma_f32 v[196:197], v[138:139], v[6:7], v[196:197]
	v_add_f32_e32 v12, v194, v195
	v_add_f32_e32 v28, v196, v197
	s_waitcnt lgkmcnt(0)
	ds_read_b128 v[134:137], v42 offset:6912
	ds_read_b128 v[130:133], v42 offset:6656
	ds_read_b64 v[142:143], v43 offset:6144
	ds_read_b128 v[122:125], v42 offset:6144
	ds_read_b128 v[126:129], v42 offset:6400
	ds_read_b128 v[138:141], v42 offset:7168
	v_pk_mul_f32 v[176:177], v[2:3], v[166:167]
	v_pk_mul_f32 v[178:179], v[6:7], v[166:167]
	v_pk_fma_f32 v[176:177], v[4:5], v[168:169], v[176:177]
	v_pk_fma_f32 v[178:179], v[8:9], v[168:169], v[178:179]
	v_pk_mul_f32 v[180:181], v[162:163], v[174:175] op_sel_hi:[1,0]
	v_add_f32_e32 v198, v176, v177
	v_pk_mul_f32 v[190:191], v[162:163], v[174:175] op_sel:[0,1] op_sel_hi:[1,1]
	v_add_f32_e32 v200, v178, v179
	v_pk_mul_f32 v[188:189], v[164:165], v[174:175] op_sel_hi:[1,0]
	v_add_f32_dpp v198, v198, v198 quad_perm:[1,0,3,2] row_mask:0xf bank_mask:0xf bound_ctrl:1
	v_pk_mul_f32 v[192:193], v[164:165], v[174:175] op_sel:[0,1] op_sel_hi:[1,1]
	v_add_f32_dpp v200, v200, v200 quad_perm:[1,0,3,2] row_mask:0xf bank_mask:0xf bound_ctrl:1
	v_pk_fma_f32 v[2:3], v[2:3], v[154:155], v[180:181]
	v_add_f32_dpp v198, v198, v198 quad_perm:[2,3,0,1] row_mask:0xf bank_mask:0xf bound_ctrl:1
	v_pk_fma_f32 v[6:7], v[6:7], v[154:155], v[190:191]
	v_add_f32_dpp v200, v200, v200 quad_perm:[2,3,0,1] row_mask:0xf bank_mask:0xf bound_ctrl:1
	v_pk_fma_f32 v[4:5], v[4:5], v[156:157], v[188:189]
	v_add_f32_dpp v198, v198, v198 row_half_mirror row_mask:0xf bank_mask:0xf bound_ctrl:1
	v_pk_fma_f32 v[8:9], v[8:9], v[156:157], v[192:193]
	v_add_f32_dpp v200, v200, v200 row_half_mirror row_mask:0xf bank_mask:0xf bound_ctrl:1
	s_nop 0
	v_add_f32_dpp v198, v198, v198 row_mirror row_mask:0xf bank_mask:0xf bound_ctrl:1
	s_nop 0
	v_add_f32_dpp v200, v200, v200 row_mirror row_mask:0xf bank_mask:0xf bound_ctrl:1
	v_pk_fma_f32 v[2:3], v[158:159], v[198:199], v[2:3] op_sel_hi:[1,0,1] neg_lo:[0,1,0] neg_hi:[0,1,0]
	v_pk_fma_f32 v[4:5], v[160:161], v[198:199], v[4:5] op_sel_hi:[1,0,1] neg_lo:[0,1,0] neg_hi:[0,1,0]
	v_pk_fma_f32 v[6:7], v[158:159], v[200:201], v[6:7] op_sel_hi:[1,0,1] neg_lo:[0,1,0] neg_hi:[0,1,0]
	v_pk_fma_f32 v[8:9], v[160:161], v[200:201], v[8:9] op_sel_hi:[1,0,1] neg_lo:[0,1,0] neg_hi:[0,1,0]
	v_pk_mul_f32 v[194:195], v[172:173], v[4:5]
	v_pk_mul_f32 v[196:197], v[172:173], v[8:9]
	v_pk_fma_f32 v[194:195], v[170:171], v[2:3], v[194:195]
	v_pk_fma_f32 v[196:197], v[170:171], v[6:7], v[196:197]
	v_add_f32_e32 v13, v194, v195
	v_add_f32_e32 v29, v196, v197
	s_waitcnt lgkmcnt(0)
	ds_read_b128 v[166:169], v42 offset:8448
	ds_read_b128 v[162:165], v42 offset:8192
	ds_read_b64 v[174:175], v43 offset:7680
	ds_read_b128 v[154:157], v42 offset:7680
	ds_read_b128 v[158:161], v42 offset:7936
	ds_read_b128 v[170:173], v42 offset:8704
	v_pk_mul_f32 v[176:177], v[2:3], v[134:135]
	v_pk_mul_f32 v[178:179], v[6:7], v[134:135]
	v_pk_fma_f32 v[176:177], v[4:5], v[136:137], v[176:177]
	v_pk_fma_f32 v[178:179], v[8:9], v[136:137], v[178:179]
	v_pk_mul_f32 v[180:181], v[130:131], v[142:143] op_sel_hi:[1,0]
	v_add_f32_e32 v198, v176, v177
	v_pk_mul_f32 v[190:191], v[130:131], v[142:143] op_sel:[0,1] op_sel_hi:[1,1]
	v_add_f32_e32 v200, v178, v179
	v_pk_mul_f32 v[188:189], v[132:133], v[142:143] op_sel_hi:[1,0]
	v_add_f32_dpp v198, v198, v198 quad_perm:[1,0,3,2] row_mask:0xf bank_mask:0xf bound_ctrl:1
	v_pk_mul_f32 v[192:193], v[132:133], v[142:143] op_sel:[0,1] op_sel_hi:[1,1]
	v_add_f32_dpp v200, v200, v200 quad_perm:[1,0,3,2] row_mask:0xf bank_mask:0xf bound_ctrl:1
	v_pk_fma_f32 v[2:3], v[2:3], v[122:123], v[180:181]
	v_add_f32_dpp v198, v198, v198 quad_perm:[2,3,0,1] row_mask:0xf bank_mask:0xf bound_ctrl:1
	v_pk_fma_f32 v[6:7], v[6:7], v[122:123], v[190:191]
	v_add_f32_dpp v200, v200, v200 quad_perm:[2,3,0,1] row_mask:0xf bank_mask:0xf bound_ctrl:1
	v_pk_fma_f32 v[4:5], v[4:5], v[124:125], v[188:189]
	v_add_f32_dpp v198, v198, v198 row_half_mirror row_mask:0xf bank_mask:0xf bound_ctrl:1
	v_pk_fma_f32 v[8:9], v[8:9], v[124:125], v[192:193]
	v_add_f32_dpp v200, v200, v200 row_half_mirror row_mask:0xf bank_mask:0xf bound_ctrl:1
	s_nop 0
	v_add_f32_dpp v198, v198, v198 row_mirror row_mask:0xf bank_mask:0xf bound_ctrl:1
	s_nop 0
	v_add_f32_dpp v200, v200, v200 row_mirror row_mask:0xf bank_mask:0xf bound_ctrl:1
	v_pk_fma_f32 v[2:3], v[126:127], v[198:199], v[2:3] op_sel_hi:[1,0,1] neg_lo:[0,1,0] neg_hi:[0,1,0]
	v_pk_fma_f32 v[4:5], v[128:129], v[198:199], v[4:5] op_sel_hi:[1,0,1] neg_lo:[0,1,0] neg_hi:[0,1,0]
	v_pk_fma_f32 v[6:7], v[126:127], v[200:201], v[6:7] op_sel_hi:[1,0,1] neg_lo:[0,1,0] neg_hi:[0,1,0]
	v_pk_fma_f32 v[8:9], v[128:129], v[200:201], v[8:9] op_sel_hi:[1,0,1] neg_lo:[0,1,0] neg_hi:[0,1,0]
	v_pk_mul_f32 v[194:195], v[140:141], v[4:5]
	v_pk_mul_f32 v[196:197], v[140:141], v[8:9]
	v_pk_fma_f32 v[194:195], v[138:139], v[2:3], v[194:195]
	v_pk_fma_f32 v[196:197], v[138:139], v[6:7], v[196:197]
	v_add_f32_e32 v14, v194, v195
	v_add_f32_e32 v30, v196, v197
	s_waitcnt lgkmcnt(0)
	ds_read_b128 v[134:137], v42 offset:9984
	ds_read_b128 v[130:133], v42 offset:9728
	ds_read_b64 v[142:143], v43 offset:9216
	ds_read_b128 v[122:125], v42 offset:9216
	ds_read_b128 v[126:129], v42 offset:9472
	ds_read_b128 v[138:141], v42 offset:10240
	v_pk_mul_f32 v[176:177], v[2:3], v[166:167]
	v_pk_mul_f32 v[178:179], v[6:7], v[166:167]
	v_pk_fma_f32 v[176:177], v[4:5], v[168:169], v[176:177]
	v_pk_fma_f32 v[178:179], v[8:9], v[168:169], v[178:179]
	v_pk_mul_f32 v[180:181], v[162:163], v[174:175] op_sel_hi:[1,0]
	v_add_f32_e32 v198, v176, v177
	v_pk_mul_f32 v[190:191], v[162:163], v[174:175] op_sel:[0,1] op_sel_hi:[1,1]
	v_add_f32_e32 v200, v178, v179
	v_pk_mul_f32 v[188:189], v[164:165], v[174:175] op_sel_hi:[1,0]
	v_add_f32_dpp v198, v198, v198 quad_perm:[1,0,3,2] row_mask:0xf bank_mask:0xf bound_ctrl:1
	v_pk_mul_f32 v[192:193], v[164:165], v[174:175] op_sel:[0,1] op_sel_hi:[1,1]
	v_add_f32_dpp v200, v200, v200 quad_perm:[1,0,3,2] row_mask:0xf bank_mask:0xf bound_ctrl:1
	v_pk_fma_f32 v[2:3], v[2:3], v[154:155], v[180:181]
	v_add_f32_dpp v198, v198, v198 quad_perm:[2,3,0,1] row_mask:0xf bank_mask:0xf bound_ctrl:1
	v_pk_fma_f32 v[6:7], v[6:7], v[154:155], v[190:191]
	v_add_f32_dpp v200, v200, v200 quad_perm:[2,3,0,1] row_mask:0xf bank_mask:0xf bound_ctrl:1
	v_pk_fma_f32 v[4:5], v[4:5], v[156:157], v[188:189]
	v_add_f32_dpp v198, v198, v198 row_half_mirror row_mask:0xf bank_mask:0xf bound_ctrl:1
	v_pk_fma_f32 v[8:9], v[8:9], v[156:157], v[192:193]
	v_add_f32_dpp v200, v200, v200 row_half_mirror row_mask:0xf bank_mask:0xf bound_ctrl:1
	s_nop 0
	v_add_f32_dpp v198, v198, v198 row_mirror row_mask:0xf bank_mask:0xf bound_ctrl:1
	s_nop 0
	v_add_f32_dpp v200, v200, v200 row_mirror row_mask:0xf bank_mask:0xf bound_ctrl:1
	v_pk_fma_f32 v[2:3], v[158:159], v[198:199], v[2:3] op_sel_hi:[1,0,1] neg_lo:[0,1,0] neg_hi:[0,1,0]
	v_pk_fma_f32 v[4:5], v[160:161], v[198:199], v[4:5] op_sel_hi:[1,0,1] neg_lo:[0,1,0] neg_hi:[0,1,0]
	v_pk_fma_f32 v[6:7], v[158:159], v[200:201], v[6:7] op_sel_hi:[1,0,1] neg_lo:[0,1,0] neg_hi:[0,1,0]
	v_pk_fma_f32 v[8:9], v[160:161], v[200:201], v[8:9] op_sel_hi:[1,0,1] neg_lo:[0,1,0] neg_hi:[0,1,0]
	v_pk_mul_f32 v[194:195], v[172:173], v[4:5]
	v_pk_mul_f32 v[196:197], v[172:173], v[8:9]
	v_pk_fma_f32 v[194:195], v[170:171], v[2:3], v[194:195]
	v_pk_fma_f32 v[196:197], v[170:171], v[6:7], v[196:197]
	v_add_f32_e32 v15, v194, v195
	v_add_f32_e32 v31, v196, v197
	s_waitcnt lgkmcnt(0)
	ds_read_b128 v[166:169], v42 offset:11520
	ds_read_b128 v[162:165], v42 offset:11264
	ds_read_b64 v[174:175], v43 offset:10752
	ds_read_b128 v[154:157], v42 offset:10752
	ds_read_b128 v[158:161], v42 offset:11008
	ds_read_b128 v[170:173], v42 offset:11776
	v_pk_mul_f32 v[176:177], v[2:3], v[134:135]
	v_pk_mul_f32 v[178:179], v[6:7], v[134:135]
	v_pk_fma_f32 v[176:177], v[4:5], v[136:137], v[176:177]
	v_pk_fma_f32 v[178:179], v[8:9], v[136:137], v[178:179]
	v_pk_mul_f32 v[180:181], v[130:131], v[142:143] op_sel_hi:[1,0]
	v_add_f32_e32 v198, v176, v177
	v_pk_mul_f32 v[190:191], v[130:131], v[142:143] op_sel:[0,1] op_sel_hi:[1,1]
	v_add_f32_e32 v200, v178, v179
	v_pk_mul_f32 v[188:189], v[132:133], v[142:143] op_sel_hi:[1,0]
	v_add_f32_dpp v198, v198, v198 quad_perm:[1,0,3,2] row_mask:0xf bank_mask:0xf bound_ctrl:1
	v_pk_mul_f32 v[192:193], v[132:133], v[142:143] op_sel:[0,1] op_sel_hi:[1,1]
	v_add_f32_dpp v200, v200, v200 quad_perm:[1,0,3,2] row_mask:0xf bank_mask:0xf bound_ctrl:1
	v_pk_fma_f32 v[2:3], v[2:3], v[122:123], v[180:181]
	v_add_f32_dpp v198, v198, v198 quad_perm:[2,3,0,1] row_mask:0xf bank_mask:0xf bound_ctrl:1
	v_pk_fma_f32 v[6:7], v[6:7], v[122:123], v[190:191]
	v_add_f32_dpp v200, v200, v200 quad_perm:[2,3,0,1] row_mask:0xf bank_mask:0xf bound_ctrl:1
	v_pk_fma_f32 v[4:5], v[4:5], v[124:125], v[188:189]
	v_add_f32_dpp v198, v198, v198 row_half_mirror row_mask:0xf bank_mask:0xf bound_ctrl:1
	v_pk_fma_f32 v[8:9], v[8:9], v[124:125], v[192:193]
	v_add_f32_dpp v200, v200, v200 row_half_mirror row_mask:0xf bank_mask:0xf bound_ctrl:1
	s_nop 0
	v_add_f32_dpp v198, v198, v198 row_mirror row_mask:0xf bank_mask:0xf bound_ctrl:1
	s_nop 0
	v_add_f32_dpp v200, v200, v200 row_mirror row_mask:0xf bank_mask:0xf bound_ctrl:1
	v_pk_fma_f32 v[2:3], v[126:127], v[198:199], v[2:3] op_sel_hi:[1,0,1] neg_lo:[0,1,0] neg_hi:[0,1,0]
	v_pk_fma_f32 v[4:5], v[128:129], v[198:199], v[4:5] op_sel_hi:[1,0,1] neg_lo:[0,1,0] neg_hi:[0,1,0]
	v_pk_fma_f32 v[6:7], v[126:127], v[200:201], v[6:7] op_sel_hi:[1,0,1] neg_lo:[0,1,0] neg_hi:[0,1,0]
	v_pk_fma_f32 v[8:9], v[128:129], v[200:201], v[8:9] op_sel_hi:[1,0,1] neg_lo:[0,1,0] neg_hi:[0,1,0]
	v_pk_mul_f32 v[194:195], v[140:141], v[4:5]
	v_pk_mul_f32 v[196:197], v[140:141], v[8:9]
	v_pk_fma_f32 v[194:195], v[138:139], v[2:3], v[194:195]
	v_pk_fma_f32 v[196:197], v[138:139], v[6:7], v[196:197]
	v_add_f32_e32 v16, v194, v195
	v_add_f32_e32 v32, v196, v197
	s_waitcnt lgkmcnt(0)
	ds_read_b128 v[134:137], v42 offset:13056
	ds_read_b128 v[130:133], v42 offset:12800
	ds_read_b64 v[142:143], v43 offset:12288
	ds_read_b128 v[122:125], v42 offset:12288
	ds_read_b128 v[126:129], v42 offset:12544
	ds_read_b128 v[138:141], v42 offset:13312
	v_pk_mul_f32 v[176:177], v[2:3], v[166:167]
	v_pk_mul_f32 v[178:179], v[6:7], v[166:167]
	v_pk_fma_f32 v[176:177], v[4:5], v[168:169], v[176:177]
	v_pk_fma_f32 v[178:179], v[8:9], v[168:169], v[178:179]
	v_pk_mul_f32 v[180:181], v[162:163], v[174:175] op_sel_hi:[1,0]
	v_add_f32_e32 v198, v176, v177
	v_pk_mul_f32 v[190:191], v[162:163], v[174:175] op_sel:[0,1] op_sel_hi:[1,1]
	v_add_f32_e32 v200, v178, v179
	v_pk_mul_f32 v[188:189], v[164:165], v[174:175] op_sel_hi:[1,0]
	v_add_f32_dpp v198, v198, v198 quad_perm:[1,0,3,2] row_mask:0xf bank_mask:0xf bound_ctrl:1
	v_pk_mul_f32 v[192:193], v[164:165], v[174:175] op_sel:[0,1] op_sel_hi:[1,1]
	v_add_f32_dpp v200, v200, v200 quad_perm:[1,0,3,2] row_mask:0xf bank_mask:0xf bound_ctrl:1
	v_pk_fma_f32 v[2:3], v[2:3], v[154:155], v[180:181]
	v_add_f32_dpp v198, v198, v198 quad_perm:[2,3,0,1] row_mask:0xf bank_mask:0xf bound_ctrl:1
	v_pk_fma_f32 v[6:7], v[6:7], v[154:155], v[190:191]
	v_add_f32_dpp v200, v200, v200 quad_perm:[2,3,0,1] row_mask:0xf bank_mask:0xf bound_ctrl:1
	v_pk_fma_f32 v[4:5], v[4:5], v[156:157], v[188:189]
	v_add_f32_dpp v198, v198, v198 row_half_mirror row_mask:0xf bank_mask:0xf bound_ctrl:1
	v_pk_fma_f32 v[8:9], v[8:9], v[156:157], v[192:193]
	v_add_f32_dpp v200, v200, v200 row_half_mirror row_mask:0xf bank_mask:0xf bound_ctrl:1
	s_nop 0
	v_add_f32_dpp v198, v198, v198 row_mirror row_mask:0xf bank_mask:0xf bound_ctrl:1
	s_nop 0
	v_add_f32_dpp v200, v200, v200 row_mirror row_mask:0xf bank_mask:0xf bound_ctrl:1
	v_pk_fma_f32 v[2:3], v[158:159], v[198:199], v[2:3] op_sel_hi:[1,0,1] neg_lo:[0,1,0] neg_hi:[0,1,0]
	v_pk_fma_f32 v[4:5], v[160:161], v[198:199], v[4:5] op_sel_hi:[1,0,1] neg_lo:[0,1,0] neg_hi:[0,1,0]
	v_pk_fma_f32 v[6:7], v[158:159], v[200:201], v[6:7] op_sel_hi:[1,0,1] neg_lo:[0,1,0] neg_hi:[0,1,0]
	v_pk_fma_f32 v[8:9], v[160:161], v[200:201], v[8:9] op_sel_hi:[1,0,1] neg_lo:[0,1,0] neg_hi:[0,1,0]
	v_pk_mul_f32 v[194:195], v[172:173], v[4:5]
	v_pk_mul_f32 v[196:197], v[172:173], v[8:9]
	v_pk_fma_f32 v[194:195], v[170:171], v[2:3], v[194:195]
	v_pk_fma_f32 v[196:197], v[170:171], v[6:7], v[196:197]
	v_add_f32_e32 v17, v194, v195
	v_add_f32_e32 v33, v196, v197
	s_waitcnt lgkmcnt(0)
	ds_read_b128 v[166:169], v42 offset:14592
	ds_read_b128 v[162:165], v42 offset:14336
	ds_read_b64 v[174:175], v43 offset:13824
	ds_read_b128 v[154:157], v42 offset:13824
	ds_read_b128 v[158:161], v42 offset:14080
	ds_read_b128 v[170:173], v42 offset:14848
	v_pk_mul_f32 v[176:177], v[2:3], v[134:135]
	v_pk_mul_f32 v[178:179], v[6:7], v[134:135]
	v_pk_fma_f32 v[176:177], v[4:5], v[136:137], v[176:177]
	v_pk_fma_f32 v[178:179], v[8:9], v[136:137], v[178:179]
	v_pk_mul_f32 v[180:181], v[130:131], v[142:143] op_sel_hi:[1,0]
	v_add_f32_e32 v198, v176, v177
	v_pk_mul_f32 v[190:191], v[130:131], v[142:143] op_sel:[0,1] op_sel_hi:[1,1]
	v_add_f32_e32 v200, v178, v179
	v_pk_mul_f32 v[188:189], v[132:133], v[142:143] op_sel_hi:[1,0]
	v_add_f32_dpp v198, v198, v198 quad_perm:[1,0,3,2] row_mask:0xf bank_mask:0xf bound_ctrl:1
	v_pk_mul_f32 v[192:193], v[132:133], v[142:143] op_sel:[0,1] op_sel_hi:[1,1]
	v_add_f32_dpp v200, v200, v200 quad_perm:[1,0,3,2] row_mask:0xf bank_mask:0xf bound_ctrl:1
	v_pk_fma_f32 v[2:3], v[2:3], v[122:123], v[180:181]
	v_add_f32_dpp v198, v198, v198 quad_perm:[2,3,0,1] row_mask:0xf bank_mask:0xf bound_ctrl:1
	v_pk_fma_f32 v[6:7], v[6:7], v[122:123], v[190:191]
	v_add_f32_dpp v200, v200, v200 quad_perm:[2,3,0,1] row_mask:0xf bank_mask:0xf bound_ctrl:1
	v_pk_fma_f32 v[4:5], v[4:5], v[124:125], v[188:189]
	v_add_f32_dpp v198, v198, v198 row_half_mirror row_mask:0xf bank_mask:0xf bound_ctrl:1
	v_pk_fma_f32 v[8:9], v[8:9], v[124:125], v[192:193]
	v_add_f32_dpp v200, v200, v200 row_half_mirror row_mask:0xf bank_mask:0xf bound_ctrl:1
	s_nop 0
	v_add_f32_dpp v198, v198, v198 row_mirror row_mask:0xf bank_mask:0xf bound_ctrl:1
	s_nop 0
	v_add_f32_dpp v200, v200, v200 row_mirror row_mask:0xf bank_mask:0xf bound_ctrl:1
	v_pk_fma_f32 v[2:3], v[126:127], v[198:199], v[2:3] op_sel_hi:[1,0,1] neg_lo:[0,1,0] neg_hi:[0,1,0]
	v_pk_fma_f32 v[4:5], v[128:129], v[198:199], v[4:5] op_sel_hi:[1,0,1] neg_lo:[0,1,0] neg_hi:[0,1,0]
	v_pk_fma_f32 v[6:7], v[126:127], v[200:201], v[6:7] op_sel_hi:[1,0,1] neg_lo:[0,1,0] neg_hi:[0,1,0]
	v_pk_fma_f32 v[8:9], v[128:129], v[200:201], v[8:9] op_sel_hi:[1,0,1] neg_lo:[0,1,0] neg_hi:[0,1,0]
	v_pk_mul_f32 v[194:195], v[140:141], v[4:5]
	v_pk_mul_f32 v[196:197], v[140:141], v[8:9]
	v_pk_fma_f32 v[194:195], v[138:139], v[2:3], v[194:195]
	v_pk_fma_f32 v[196:197], v[138:139], v[6:7], v[196:197]
	v_add_f32_e32 v18, v194, v195
	v_add_f32_e32 v34, v196, v197
	s_waitcnt lgkmcnt(0)
	ds_read_b128 v[134:137], v42 offset:16128
	ds_read_b128 v[130:133], v42 offset:15872
	ds_read_b64 v[142:143], v43 offset:15360
	ds_read_b128 v[122:125], v42 offset:15360
	ds_read_b128 v[126:129], v42 offset:15616
	ds_read_b128 v[138:141], v42 offset:16384
	v_pk_mul_f32 v[176:177], v[2:3], v[166:167]
	v_pk_mul_f32 v[178:179], v[6:7], v[166:167]
	v_pk_fma_f32 v[176:177], v[4:5], v[168:169], v[176:177]
	v_pk_fma_f32 v[178:179], v[8:9], v[168:169], v[178:179]
	v_pk_mul_f32 v[180:181], v[162:163], v[174:175] op_sel_hi:[1,0]
	v_add_f32_e32 v198, v176, v177
	v_pk_mul_f32 v[190:191], v[162:163], v[174:175] op_sel:[0,1] op_sel_hi:[1,1]
	v_add_f32_e32 v200, v178, v179
	v_pk_mul_f32 v[188:189], v[164:165], v[174:175] op_sel_hi:[1,0]
	v_add_f32_dpp v198, v198, v198 quad_perm:[1,0,3,2] row_mask:0xf bank_mask:0xf bound_ctrl:1
	v_pk_mul_f32 v[192:193], v[164:165], v[174:175] op_sel:[0,1] op_sel_hi:[1,1]
	v_add_f32_dpp v200, v200, v200 quad_perm:[1,0,3,2] row_mask:0xf bank_mask:0xf bound_ctrl:1
	v_pk_fma_f32 v[2:3], v[2:3], v[154:155], v[180:181]
	v_add_f32_dpp v198, v198, v198 quad_perm:[2,3,0,1] row_mask:0xf bank_mask:0xf bound_ctrl:1
	v_pk_fma_f32 v[6:7], v[6:7], v[154:155], v[190:191]
	v_add_f32_dpp v200, v200, v200 quad_perm:[2,3,0,1] row_mask:0xf bank_mask:0xf bound_ctrl:1
	v_pk_fma_f32 v[4:5], v[4:5], v[156:157], v[188:189]
	v_add_f32_dpp v198, v198, v198 row_half_mirror row_mask:0xf bank_mask:0xf bound_ctrl:1
	v_pk_fma_f32 v[8:9], v[8:9], v[156:157], v[192:193]
	v_add_f32_dpp v200, v200, v200 row_half_mirror row_mask:0xf bank_mask:0xf bound_ctrl:1
	s_nop 0
	v_add_f32_dpp v198, v198, v198 row_mirror row_mask:0xf bank_mask:0xf bound_ctrl:1
	s_nop 0
	v_add_f32_dpp v200, v200, v200 row_mirror row_mask:0xf bank_mask:0xf bound_ctrl:1
	v_pk_fma_f32 v[2:3], v[158:159], v[198:199], v[2:3] op_sel_hi:[1,0,1] neg_lo:[0,1,0] neg_hi:[0,1,0]
	v_pk_fma_f32 v[4:5], v[160:161], v[198:199], v[4:5] op_sel_hi:[1,0,1] neg_lo:[0,1,0] neg_hi:[0,1,0]
	v_pk_fma_f32 v[6:7], v[158:159], v[200:201], v[6:7] op_sel_hi:[1,0,1] neg_lo:[0,1,0] neg_hi:[0,1,0]
	v_pk_fma_f32 v[8:9], v[160:161], v[200:201], v[8:9] op_sel_hi:[1,0,1] neg_lo:[0,1,0] neg_hi:[0,1,0]
	v_pk_mul_f32 v[194:195], v[172:173], v[4:5]
	v_pk_mul_f32 v[196:197], v[172:173], v[8:9]
	v_pk_fma_f32 v[194:195], v[170:171], v[2:3], v[194:195]
	v_pk_fma_f32 v[196:197], v[170:171], v[6:7], v[196:197]
	v_add_f32_e32 v19, v194, v195
	v_add_f32_e32 v35, v196, v197
	s_waitcnt lgkmcnt(0)
	ds_read_b128 v[166:169], v42 offset:17664
	ds_read_b128 v[162:165], v42 offset:17408
	ds_read_b64 v[174:175], v43 offset:16896
	ds_read_b128 v[154:157], v42 offset:16896
	ds_read_b128 v[158:161], v42 offset:17152
	ds_read_b128 v[170:173], v42 offset:17920
	v_pk_mul_f32 v[176:177], v[2:3], v[134:135]
	v_pk_mul_f32 v[178:179], v[6:7], v[134:135]
	v_pk_fma_f32 v[176:177], v[4:5], v[136:137], v[176:177]
	v_pk_fma_f32 v[178:179], v[8:9], v[136:137], v[178:179]
	v_pk_mul_f32 v[180:181], v[130:131], v[142:143] op_sel_hi:[1,0]
	v_add_f32_e32 v198, v176, v177
	v_pk_mul_f32 v[190:191], v[130:131], v[142:143] op_sel:[0,1] op_sel_hi:[1,1]
	v_add_f32_e32 v200, v178, v179
	v_pk_mul_f32 v[188:189], v[132:133], v[142:143] op_sel_hi:[1,0]
	v_add_f32_dpp v198, v198, v198 quad_perm:[1,0,3,2] row_mask:0xf bank_mask:0xf bound_ctrl:1
	v_pk_mul_f32 v[192:193], v[132:133], v[142:143] op_sel:[0,1] op_sel_hi:[1,1]
	v_add_f32_dpp v200, v200, v200 quad_perm:[1,0,3,2] row_mask:0xf bank_mask:0xf bound_ctrl:1
	v_pk_fma_f32 v[2:3], v[2:3], v[122:123], v[180:181]
	v_add_f32_dpp v198, v198, v198 quad_perm:[2,3,0,1] row_mask:0xf bank_mask:0xf bound_ctrl:1
	v_pk_fma_f32 v[6:7], v[6:7], v[122:123], v[190:191]
	v_add_f32_dpp v200, v200, v200 quad_perm:[2,3,0,1] row_mask:0xf bank_mask:0xf bound_ctrl:1
	v_pk_fma_f32 v[4:5], v[4:5], v[124:125], v[188:189]
	v_add_f32_dpp v198, v198, v198 row_half_mirror row_mask:0xf bank_mask:0xf bound_ctrl:1
	v_pk_fma_f32 v[8:9], v[8:9], v[124:125], v[192:193]
	v_add_f32_dpp v200, v200, v200 row_half_mirror row_mask:0xf bank_mask:0xf bound_ctrl:1
	s_nop 0
	v_add_f32_dpp v198, v198, v198 row_mirror row_mask:0xf bank_mask:0xf bound_ctrl:1
	s_nop 0
	v_add_f32_dpp v200, v200, v200 row_mirror row_mask:0xf bank_mask:0xf bound_ctrl:1
	v_pk_fma_f32 v[2:3], v[126:127], v[198:199], v[2:3] op_sel_hi:[1,0,1] neg_lo:[0,1,0] neg_hi:[0,1,0]
	v_pk_fma_f32 v[4:5], v[128:129], v[198:199], v[4:5] op_sel_hi:[1,0,1] neg_lo:[0,1,0] neg_hi:[0,1,0]
	v_pk_fma_f32 v[6:7], v[126:127], v[200:201], v[6:7] op_sel_hi:[1,0,1] neg_lo:[0,1,0] neg_hi:[0,1,0]
	v_pk_fma_f32 v[8:9], v[128:129], v[200:201], v[8:9] op_sel_hi:[1,0,1] neg_lo:[0,1,0] neg_hi:[0,1,0]
	v_pk_mul_f32 v[194:195], v[140:141], v[4:5]
	v_pk_mul_f32 v[196:197], v[140:141], v[8:9]
	v_pk_fma_f32 v[194:195], v[138:139], v[2:3], v[194:195]
	v_pk_fma_f32 v[196:197], v[138:139], v[6:7], v[196:197]
	v_add_f32_e32 v20, v194, v195
	v_add_f32_e32 v36, v196, v197
	s_waitcnt lgkmcnt(0)
	ds_read_b128 v[134:137], v42 offset:19200
	ds_read_b128 v[130:133], v42 offset:18944
	ds_read_b64 v[142:143], v43 offset:18432
	ds_read_b128 v[122:125], v42 offset:18432
	ds_read_b128 v[126:129], v42 offset:18688
	ds_read_b128 v[138:141], v42 offset:19456
	v_pk_mul_f32 v[176:177], v[2:3], v[166:167]
	v_pk_mul_f32 v[178:179], v[6:7], v[166:167]
	v_pk_fma_f32 v[176:177], v[4:5], v[168:169], v[176:177]
	v_pk_fma_f32 v[178:179], v[8:9], v[168:169], v[178:179]
	v_pk_mul_f32 v[180:181], v[162:163], v[174:175] op_sel_hi:[1,0]
	v_add_f32_e32 v198, v176, v177
	v_pk_mul_f32 v[190:191], v[162:163], v[174:175] op_sel:[0,1] op_sel_hi:[1,1]
	v_add_f32_e32 v200, v178, v179
	v_pk_mul_f32 v[188:189], v[164:165], v[174:175] op_sel_hi:[1,0]
	v_add_f32_dpp v198, v198, v198 quad_perm:[1,0,3,2] row_mask:0xf bank_mask:0xf bound_ctrl:1
	v_pk_mul_f32 v[192:193], v[164:165], v[174:175] op_sel:[0,1] op_sel_hi:[1,1]
	v_add_f32_dpp v200, v200, v200 quad_perm:[1,0,3,2] row_mask:0xf bank_mask:0xf bound_ctrl:1
	v_pk_fma_f32 v[2:3], v[2:3], v[154:155], v[180:181]
	v_add_f32_dpp v198, v198, v198 quad_perm:[2,3,0,1] row_mask:0xf bank_mask:0xf bound_ctrl:1
	v_pk_fma_f32 v[6:7], v[6:7], v[154:155], v[190:191]
	v_add_f32_dpp v200, v200, v200 quad_perm:[2,3,0,1] row_mask:0xf bank_mask:0xf bound_ctrl:1
	v_pk_fma_f32 v[4:5], v[4:5], v[156:157], v[188:189]
	v_add_f32_dpp v198, v198, v198 row_half_mirror row_mask:0xf bank_mask:0xf bound_ctrl:1
	v_pk_fma_f32 v[8:9], v[8:9], v[156:157], v[192:193]
	v_add_f32_dpp v200, v200, v200 row_half_mirror row_mask:0xf bank_mask:0xf bound_ctrl:1
	s_nop 0
	v_add_f32_dpp v198, v198, v198 row_mirror row_mask:0xf bank_mask:0xf bound_ctrl:1
	s_nop 0
	v_add_f32_dpp v200, v200, v200 row_mirror row_mask:0xf bank_mask:0xf bound_ctrl:1
	v_pk_fma_f32 v[2:3], v[158:159], v[198:199], v[2:3] op_sel_hi:[1,0,1] neg_lo:[0,1,0] neg_hi:[0,1,0]
	v_pk_fma_f32 v[4:5], v[160:161], v[198:199], v[4:5] op_sel_hi:[1,0,1] neg_lo:[0,1,0] neg_hi:[0,1,0]
	v_pk_fma_f32 v[6:7], v[158:159], v[200:201], v[6:7] op_sel_hi:[1,0,1] neg_lo:[0,1,0] neg_hi:[0,1,0]
	v_pk_fma_f32 v[8:9], v[160:161], v[200:201], v[8:9] op_sel_hi:[1,0,1] neg_lo:[0,1,0] neg_hi:[0,1,0]
	v_pk_mul_f32 v[194:195], v[172:173], v[4:5]
	v_pk_mul_f32 v[196:197], v[172:173], v[8:9]
	v_pk_fma_f32 v[194:195], v[170:171], v[2:3], v[194:195]
	v_pk_fma_f32 v[196:197], v[170:171], v[6:7], v[196:197]
	v_add_f32_e32 v21, v194, v195
	v_add_f32_e32 v37, v196, v197
	s_waitcnt lgkmcnt(0)
	ds_read_b128 v[166:169], v42 offset:20736
	ds_read_b128 v[162:165], v42 offset:20480
	ds_read_b64 v[174:175], v43 offset:19968
	ds_read_b128 v[154:157], v42 offset:19968
	ds_read_b128 v[158:161], v42 offset:20224
	ds_read_b128 v[170:173], v42 offset:20992
	v_pk_mul_f32 v[176:177], v[2:3], v[134:135]
	v_pk_mul_f32 v[178:179], v[6:7], v[134:135]
	v_pk_fma_f32 v[176:177], v[4:5], v[136:137], v[176:177]
	v_pk_fma_f32 v[178:179], v[8:9], v[136:137], v[178:179]
	v_pk_mul_f32 v[180:181], v[130:131], v[142:143] op_sel_hi:[1,0]
	v_add_f32_e32 v198, v176, v177
	v_pk_mul_f32 v[190:191], v[130:131], v[142:143] op_sel:[0,1] op_sel_hi:[1,1]
	v_add_f32_e32 v200, v178, v179
	v_pk_mul_f32 v[188:189], v[132:133], v[142:143] op_sel_hi:[1,0]
	v_add_f32_dpp v198, v198, v198 quad_perm:[1,0,3,2] row_mask:0xf bank_mask:0xf bound_ctrl:1
	v_pk_mul_f32 v[192:193], v[132:133], v[142:143] op_sel:[0,1] op_sel_hi:[1,1]
	v_add_f32_dpp v200, v200, v200 quad_perm:[1,0,3,2] row_mask:0xf bank_mask:0xf bound_ctrl:1
	v_pk_fma_f32 v[2:3], v[2:3], v[122:123], v[180:181]
	v_add_f32_dpp v198, v198, v198 quad_perm:[2,3,0,1] row_mask:0xf bank_mask:0xf bound_ctrl:1
	v_pk_fma_f32 v[6:7], v[6:7], v[122:123], v[190:191]
	v_add_f32_dpp v200, v200, v200 quad_perm:[2,3,0,1] row_mask:0xf bank_mask:0xf bound_ctrl:1
	v_pk_fma_f32 v[4:5], v[4:5], v[124:125], v[188:189]
	v_add_f32_dpp v198, v198, v198 row_half_mirror row_mask:0xf bank_mask:0xf bound_ctrl:1
	v_pk_fma_f32 v[8:9], v[8:9], v[124:125], v[192:193]
	v_add_f32_dpp v200, v200, v200 row_half_mirror row_mask:0xf bank_mask:0xf bound_ctrl:1
	s_nop 0
	v_add_f32_dpp v198, v198, v198 row_mirror row_mask:0xf bank_mask:0xf bound_ctrl:1
	s_nop 0
	v_add_f32_dpp v200, v200, v200 row_mirror row_mask:0xf bank_mask:0xf bound_ctrl:1
	v_pk_fma_f32 v[2:3], v[126:127], v[198:199], v[2:3] op_sel_hi:[1,0,1] neg_lo:[0,1,0] neg_hi:[0,1,0]
	v_pk_fma_f32 v[4:5], v[128:129], v[198:199], v[4:5] op_sel_hi:[1,0,1] neg_lo:[0,1,0] neg_hi:[0,1,0]
	v_pk_fma_f32 v[6:7], v[126:127], v[200:201], v[6:7] op_sel_hi:[1,0,1] neg_lo:[0,1,0] neg_hi:[0,1,0]
	v_pk_fma_f32 v[8:9], v[128:129], v[200:201], v[8:9] op_sel_hi:[1,0,1] neg_lo:[0,1,0] neg_hi:[0,1,0]
	v_pk_mul_f32 v[194:195], v[140:141], v[4:5]
	v_pk_mul_f32 v[196:197], v[140:141], v[8:9]
	v_pk_fma_f32 v[194:195], v[138:139], v[2:3], v[194:195]
	v_pk_fma_f32 v[196:197], v[138:139], v[6:7], v[196:197]
	v_add_f32_e32 v22, v194, v195
	v_add_f32_e32 v38, v196, v197
	s_waitcnt lgkmcnt(0)
	ds_read_b128 v[134:137], v42 offset:22272
	ds_read_b128 v[130:133], v42 offset:22016
	ds_read_b64 v[142:143], v43 offset:21504
	ds_read_b128 v[122:125], v42 offset:21504
	ds_read_b128 v[126:129], v42 offset:21760
	ds_read_b128 v[138:141], v42 offset:22528
	v_pk_mul_f32 v[176:177], v[2:3], v[166:167]
	v_pk_mul_f32 v[178:179], v[6:7], v[166:167]
	v_pk_fma_f32 v[176:177], v[4:5], v[168:169], v[176:177]
	v_pk_fma_f32 v[178:179], v[8:9], v[168:169], v[178:179]
	v_pk_mul_f32 v[180:181], v[162:163], v[174:175] op_sel_hi:[1,0]
	v_add_f32_e32 v198, v176, v177
	v_pk_mul_f32 v[190:191], v[162:163], v[174:175] op_sel:[0,1] op_sel_hi:[1,1]
	v_add_f32_e32 v200, v178, v179
	v_pk_mul_f32 v[188:189], v[164:165], v[174:175] op_sel_hi:[1,0]
	v_add_f32_dpp v198, v198, v198 quad_perm:[1,0,3,2] row_mask:0xf bank_mask:0xf bound_ctrl:1
	v_pk_mul_f32 v[192:193], v[164:165], v[174:175] op_sel:[0,1] op_sel_hi:[1,1]
	v_add_f32_dpp v200, v200, v200 quad_perm:[1,0,3,2] row_mask:0xf bank_mask:0xf bound_ctrl:1
	v_pk_fma_f32 v[2:3], v[2:3], v[154:155], v[180:181]
	v_add_f32_dpp v198, v198, v198 quad_perm:[2,3,0,1] row_mask:0xf bank_mask:0xf bound_ctrl:1
	v_pk_fma_f32 v[6:7], v[6:7], v[154:155], v[190:191]
	v_add_f32_dpp v200, v200, v200 quad_perm:[2,3,0,1] row_mask:0xf bank_mask:0xf bound_ctrl:1
	v_pk_fma_f32 v[4:5], v[4:5], v[156:157], v[188:189]
	v_add_f32_dpp v198, v198, v198 row_half_mirror row_mask:0xf bank_mask:0xf bound_ctrl:1
	v_pk_fma_f32 v[8:9], v[8:9], v[156:157], v[192:193]
	v_add_f32_dpp v200, v200, v200 row_half_mirror row_mask:0xf bank_mask:0xf bound_ctrl:1
	s_nop 0
	v_add_f32_dpp v198, v198, v198 row_mirror row_mask:0xf bank_mask:0xf bound_ctrl:1
	s_nop 0
	v_add_f32_dpp v200, v200, v200 row_mirror row_mask:0xf bank_mask:0xf bound_ctrl:1
	v_pk_fma_f32 v[2:3], v[158:159], v[198:199], v[2:3] op_sel_hi:[1,0,1] neg_lo:[0,1,0] neg_hi:[0,1,0]
	v_pk_fma_f32 v[4:5], v[160:161], v[198:199], v[4:5] op_sel_hi:[1,0,1] neg_lo:[0,1,0] neg_hi:[0,1,0]
	v_pk_fma_f32 v[6:7], v[158:159], v[200:201], v[6:7] op_sel_hi:[1,0,1] neg_lo:[0,1,0] neg_hi:[0,1,0]
	v_pk_fma_f32 v[8:9], v[160:161], v[200:201], v[8:9] op_sel_hi:[1,0,1] neg_lo:[0,1,0] neg_hi:[0,1,0]
	v_pk_mul_f32 v[194:195], v[172:173], v[4:5]
	v_pk_mul_f32 v[196:197], v[172:173], v[8:9]
	v_pk_fma_f32 v[194:195], v[170:171], v[2:3], v[194:195]
	v_pk_fma_f32 v[196:197], v[170:171], v[6:7], v[196:197]
	v_add_f32_e32 v23, v194, v195
	v_add_f32_e32 v39, v196, v197
	s_waitcnt lgkmcnt(0)
	ds_read_b128 v[166:169], v42 offset:23808
	ds_read_b128 v[162:165], v42 offset:23552
	ds_read_b64 v[174:175], v43 offset:23040
	ds_read_b128 v[154:157], v42 offset:23040
	ds_read_b128 v[158:161], v42 offset:23296
	ds_read_b128 v[170:173], v42 offset:24064
	v_pk_mul_f32 v[176:177], v[2:3], v[134:135]
	v_pk_mul_f32 v[178:179], v[6:7], v[134:135]
	v_pk_fma_f32 v[176:177], v[4:5], v[136:137], v[176:177]
	v_pk_fma_f32 v[178:179], v[8:9], v[136:137], v[178:179]
	v_pk_mul_f32 v[180:181], v[130:131], v[142:143] op_sel_hi:[1,0]
	v_add_f32_e32 v198, v176, v177
	v_pk_mul_f32 v[190:191], v[130:131], v[142:143] op_sel:[0,1] op_sel_hi:[1,1]
	v_add_f32_e32 v200, v178, v179
	v_pk_mul_f32 v[188:189], v[132:133], v[142:143] op_sel_hi:[1,0]
	v_add_f32_dpp v198, v198, v198 quad_perm:[1,0,3,2] row_mask:0xf bank_mask:0xf bound_ctrl:1
	v_pk_mul_f32 v[192:193], v[132:133], v[142:143] op_sel:[0,1] op_sel_hi:[1,1]
	v_add_f32_dpp v200, v200, v200 quad_perm:[1,0,3,2] row_mask:0xf bank_mask:0xf bound_ctrl:1
	v_pk_fma_f32 v[2:3], v[2:3], v[122:123], v[180:181]
	v_add_f32_dpp v198, v198, v198 quad_perm:[2,3,0,1] row_mask:0xf bank_mask:0xf bound_ctrl:1
	v_pk_fma_f32 v[6:7], v[6:7], v[122:123], v[190:191]
	v_add_f32_dpp v200, v200, v200 quad_perm:[2,3,0,1] row_mask:0xf bank_mask:0xf bound_ctrl:1
	v_pk_fma_f32 v[4:5], v[4:5], v[124:125], v[188:189]
	v_add_f32_dpp v198, v198, v198 row_half_mirror row_mask:0xf bank_mask:0xf bound_ctrl:1
	v_pk_fma_f32 v[8:9], v[8:9], v[124:125], v[192:193]
	v_add_f32_dpp v200, v200, v200 row_half_mirror row_mask:0xf bank_mask:0xf bound_ctrl:1
	s_nop 0
	v_add_f32_dpp v198, v198, v198 row_mirror row_mask:0xf bank_mask:0xf bound_ctrl:1
	s_nop 0
	v_add_f32_dpp v200, v200, v200 row_mirror row_mask:0xf bank_mask:0xf bound_ctrl:1
	v_pk_fma_f32 v[2:3], v[126:127], v[198:199], v[2:3] op_sel_hi:[1,0,1] neg_lo:[0,1,0] neg_hi:[0,1,0]
	v_pk_fma_f32 v[4:5], v[128:129], v[198:199], v[4:5] op_sel_hi:[1,0,1] neg_lo:[0,1,0] neg_hi:[0,1,0]
	v_pk_fma_f32 v[6:7], v[126:127], v[200:201], v[6:7] op_sel_hi:[1,0,1] neg_lo:[0,1,0] neg_hi:[0,1,0]
	v_pk_fma_f32 v[8:9], v[128:129], v[200:201], v[8:9] op_sel_hi:[1,0,1] neg_lo:[0,1,0] neg_hi:[0,1,0]
	v_pk_mul_f32 v[194:195], v[140:141], v[4:5]
	v_pk_mul_f32 v[196:197], v[140:141], v[8:9]
	v_pk_fma_f32 v[194:195], v[138:139], v[2:3], v[194:195]
	v_pk_fma_f32 v[196:197], v[138:139], v[6:7], v[196:197]
	v_add_f32_e32 v24, v194, v195
	v_add_f32_e32 v40, v196, v197
	s_waitcnt lgkmcnt(0)
	ds_read_b128 v[134:137], v42 offset:25344
	ds_read_b128 v[130:133], v42 offset:25088
	ds_read_b64 v[142:143], v43 offset:24576
	ds_read_b128 v[122:125], v42 offset:24576
	ds_read_b128 v[126:129], v42 offset:24832
	ds_read_b128 v[138:141], v42 offset:25600
	v_pk_mul_f32 v[176:177], v[2:3], v[166:167]
	v_pk_mul_f32 v[178:179], v[6:7], v[166:167]
	v_pk_fma_f32 v[176:177], v[4:5], v[168:169], v[176:177]
	v_pk_fma_f32 v[178:179], v[8:9], v[168:169], v[178:179]
	v_pk_mul_f32 v[180:181], v[162:163], v[174:175] op_sel_hi:[1,0]
	v_add_f32_e32 v198, v176, v177
	v_pk_mul_f32 v[190:191], v[162:163], v[174:175] op_sel:[0,1] op_sel_hi:[1,1]
	v_add_f32_e32 v200, v178, v179
	v_pk_mul_f32 v[188:189], v[164:165], v[174:175] op_sel_hi:[1,0]
	v_add_f32_dpp v198, v198, v198 quad_perm:[1,0,3,2] row_mask:0xf bank_mask:0xf bound_ctrl:1
	v_pk_mul_f32 v[192:193], v[164:165], v[174:175] op_sel:[0,1] op_sel_hi:[1,1]
	v_add_f32_dpp v200, v200, v200 quad_perm:[1,0,3,2] row_mask:0xf bank_mask:0xf bound_ctrl:1
	v_pk_fma_f32 v[2:3], v[2:3], v[154:155], v[180:181]
	v_add_f32_dpp v198, v198, v198 quad_perm:[2,3,0,1] row_mask:0xf bank_mask:0xf bound_ctrl:1
	v_pk_fma_f32 v[6:7], v[6:7], v[154:155], v[190:191]
	v_add_f32_dpp v200, v200, v200 quad_perm:[2,3,0,1] row_mask:0xf bank_mask:0xf bound_ctrl:1
	v_pk_fma_f32 v[4:5], v[4:5], v[156:157], v[188:189]
	v_add_f32_dpp v198, v198, v198 row_half_mirror row_mask:0xf bank_mask:0xf bound_ctrl:1
	v_pk_fma_f32 v[8:9], v[8:9], v[156:157], v[192:193]
	v_add_f32_dpp v200, v200, v200 row_half_mirror row_mask:0xf bank_mask:0xf bound_ctrl:1
	s_nop 0
	v_add_f32_dpp v198, v198, v198 row_mirror row_mask:0xf bank_mask:0xf bound_ctrl:1
	s_nop 0
	v_add_f32_dpp v200, v200, v200 row_mirror row_mask:0xf bank_mask:0xf bound_ctrl:1
	v_pk_fma_f32 v[2:3], v[158:159], v[198:199], v[2:3] op_sel_hi:[1,0,1] neg_lo:[0,1,0] neg_hi:[0,1,0]
	v_pk_fma_f32 v[4:5], v[160:161], v[198:199], v[4:5] op_sel_hi:[1,0,1] neg_lo:[0,1,0] neg_hi:[0,1,0]
	v_pk_fma_f32 v[6:7], v[158:159], v[200:201], v[6:7] op_sel_hi:[1,0,1] neg_lo:[0,1,0] neg_hi:[0,1,0]
	v_pk_fma_f32 v[8:9], v[160:161], v[200:201], v[8:9] op_sel_hi:[1,0,1] neg_lo:[0,1,0] neg_hi:[0,1,0]
	v_pk_mul_f32 v[194:195], v[172:173], v[4:5]
	v_pk_mul_f32 v[196:197], v[172:173], v[8:9]
	v_pk_fma_f32 v[194:195], v[170:171], v[2:3], v[194:195]
	v_pk_fma_f32 v[196:197], v[170:171], v[6:7], v[196:197]
	v_add_f32_e32 v25, v194, v195
	v_add_f32_e32 v41, v196, v197
	v_add_f32_dpp v190, v10, v10 row_mirror row_mask:0xf bank_mask:0x3
	v_add_f32_dpp v190, v18, v18 row_mirror row_mask:0xf bank_mask:0xc
	v_add_f32_dpp v191, v11, v11 row_mirror row_mask:0xf bank_mask:0x3
	v_add_f32_dpp v191, v19, v19 row_mirror row_mask:0xf bank_mask:0xc
	v_add_f32_dpp v192, v12, v12 row_mirror row_mask:0xf bank_mask:0x3
	v_add_f32_dpp v192, v20, v20 row_mirror row_mask:0xf bank_mask:0xc
	v_add_f32_dpp v193, v13, v13 row_mirror row_mask:0xf bank_mask:0x3
	v_add_f32_dpp v193, v21, v21 row_mirror row_mask:0xf bank_mask:0xc
	v_add_f32_dpp v194, v14, v14 row_mirror row_mask:0xf bank_mask:0x3
	v_add_f32_dpp v194, v22, v22 row_mirror row_mask:0xf bank_mask:0xc
	v_add_f32_dpp v195, v15, v15 row_mirror row_mask:0xf bank_mask:0x3
	v_add_f32_dpp v195, v23, v23 row_mirror row_mask:0xf bank_mask:0xc
	v_add_f32_dpp v196, v16, v16 row_mirror row_mask:0xf bank_mask:0x3
	v_add_f32_dpp v196, v24, v24 row_mirror row_mask:0xf bank_mask:0xc
	v_add_f32_dpp v197, v17, v17 row_mirror row_mask:0xf bank_mask:0x3
	v_add_f32_dpp v197, v25, v25 row_mirror row_mask:0xf bank_mask:0xc
	v_add_f32_dpp v202, v190, v190 row_half_mirror row_mask:0xf bank_mask:0x5
	v_add_f32_dpp v202, v194, v194 row_half_mirror row_mask:0xf bank_mask:0xa
	v_add_f32_dpp v203, v191, v191 row_half_mirror row_mask:0xf bank_mask:0x5
	v_add_f32_dpp v203, v195, v195 row_half_mirror row_mask:0xf bank_mask:0xa
	v_add_f32_dpp v204, v192, v192 row_half_mirror row_mask:0xf bank_mask:0x5
	v_add_f32_dpp v204, v196, v196 row_half_mirror row_mask:0xf bank_mask:0xa
	v_add_f32_dpp v205, v193, v193 row_half_mirror row_mask:0xf bank_mask:0x5
	v_add_f32_dpp v205, v197, v197 row_half_mirror row_mask:0xf bank_mask:0xa
	v_cndmask_b32_e64 v176, v202, v204, s[84:85]
	v_cndmask_b32_e64 v177, v204, v202, s[84:85]
	v_cndmask_b32_e64 v178, v203, v205, s[84:85]
	v_cndmask_b32_e64 v179, v205, v203, s[84:85]
	s_nop 1
	v_add_f32_dpp v210, v177, v176 quad_perm:[2,3,0,1] row_mask:0xf bank_mask:0xf bound_ctrl:1
	v_add_f32_dpp v211, v179, v178 quad_perm:[2,3,0,1] row_mask:0xf bank_mask:0xf bound_ctrl:1
	s_nop 0
	v_cndmask_b32_e64 v176, v210, v211, s[88:89]
	v_cndmask_b32_e64 v177, v211, v210, s[88:89]
	s_nop 1
	v_add_f32_dpp v212, v177, v176 quad_perm:[1,0,3,2] row_mask:0xf bank_mask:0xf bound_ctrl:1
	ds_write_b32 v44, v212 offset:0
	v_add_f32_dpp v190, v26, v26 row_mirror row_mask:0xf bank_mask:0x3
	v_add_f32_dpp v190, v34, v34 row_mirror row_mask:0xf bank_mask:0xc
	v_add_f32_dpp v191, v27, v27 row_mirror row_mask:0xf bank_mask:0x3
	v_add_f32_dpp v191, v35, v35 row_mirror row_mask:0xf bank_mask:0xc
	v_add_f32_dpp v192, v28, v28 row_mirror row_mask:0xf bank_mask:0x3
	v_add_f32_dpp v192, v36, v36 row_mirror row_mask:0xf bank_mask:0xc
	v_add_f32_dpp v193, v29, v29 row_mirror row_mask:0xf bank_mask:0x3
	v_add_f32_dpp v193, v37, v37 row_mirror row_mask:0xf bank_mask:0xc
	v_add_f32_dpp v194, v30, v30 row_mirror row_mask:0xf bank_mask:0x3
	v_add_f32_dpp v194, v38, v38 row_mirror row_mask:0xf bank_mask:0xc
	v_add_f32_dpp v195, v31, v31 row_mirror row_mask:0xf bank_mask:0x3
	v_add_f32_dpp v195, v39, v39 row_mirror row_mask:0xf bank_mask:0xc
	v_add_f32_dpp v196, v32, v32 row_mirror row_mask:0xf bank_mask:0x3
	v_add_f32_dpp v196, v40, v40 row_mirror row_mask:0xf bank_mask:0xc
	v_add_f32_dpp v197, v33, v33 row_mirror row_mask:0xf bank_mask:0x3
	v_add_f32_dpp v197, v41, v41 row_mirror row_mask:0xf bank_mask:0xc
	v_add_f32_dpp v202, v190, v190 row_half_mirror row_mask:0xf bank_mask:0x5
	v_add_f32_dpp v202, v194, v194 row_half_mirror row_mask:0xf bank_mask:0xa
	v_add_f32_dpp v203, v191, v191 row_half_mirror row_mask:0xf bank_mask:0x5
	v_add_f32_dpp v203, v195, v195 row_half_mirror row_mask:0xf bank_mask:0xa
	v_add_f32_dpp v204, v192, v192 row_half_mirror row_mask:0xf bank_mask:0x5
	v_add_f32_dpp v204, v196, v196 row_half_mirror row_mask:0xf bank_mask:0xa
	v_add_f32_dpp v205, v193, v193 row_half_mirror row_mask:0xf bank_mask:0x5
	v_add_f32_dpp v205, v197, v197 row_half_mirror row_mask:0xf bank_mask:0xa
	v_cndmask_b32_e64 v176, v202, v204, s[84:85]
	v_cndmask_b32_e64 v177, v204, v202, s[84:85]
	v_cndmask_b32_e64 v178, v203, v205, s[84:85]
	v_cndmask_b32_e64 v179, v205, v203, s[84:85]
	s_nop 1
	v_add_f32_dpp v210, v177, v176 quad_perm:[2,3,0,1] row_mask:0xf bank_mask:0xf bound_ctrl:1
	v_add_f32_dpp v211, v179, v178 quad_perm:[2,3,0,1] row_mask:0xf bank_mask:0xf bound_ctrl:1
	s_nop 0
	v_cndmask_b32_e64 v176, v210, v211, s[88:89]
	v_cndmask_b32_e64 v177, v211, v210, s[88:89]
	s_nop 1
	v_add_f32_dpp v212, v177, v176 quad_perm:[1,0,3,2] row_mask:0xf bank_mask:0xf bound_ctrl:1
	ds_write_b32 v44, v212 offset:4
	s_waitcnt lgkmcnt(2)
	ds_read_b128 v[166:169], v42 offset:26880
	ds_read_b128 v[162:165], v42 offset:26624
	ds_read_b64 v[174:175], v43 offset:26112
	ds_read_b128 v[154:157], v42 offset:26112
	ds_read_b128 v[158:161], v42 offset:26368
	ds_read_b128 v[170:173], v42 offset:27136
	v_pk_mul_f32 v[176:177], v[2:3], v[134:135]
	v_pk_mul_f32 v[178:179], v[6:7], v[134:135]
	v_pk_fma_f32 v[176:177], v[4:5], v[136:137], v[176:177]
	v_pk_fma_f32 v[178:179], v[8:9], v[136:137], v[178:179]
	v_pk_mul_f32 v[180:181], v[130:131], v[142:143] op_sel_hi:[1,0]
	v_add_f32_e32 v198, v176, v177
	v_pk_mul_f32 v[190:191], v[130:131], v[142:143] op_sel:[0,1] op_sel_hi:[1,1]
	v_add_f32_e32 v200, v178, v179
	v_pk_mul_f32 v[188:189], v[132:133], v[142:143] op_sel_hi:[1,0]
	v_add_f32_dpp v198, v198, v198 quad_perm:[1,0,3,2] row_mask:0xf bank_mask:0xf bound_ctrl:1
	v_pk_mul_f32 v[192:193], v[132:133], v[142:143] op_sel:[0,1] op_sel_hi:[1,1]
	v_add_f32_dpp v200, v200, v200 quad_perm:[1,0,3,2] row_mask:0xf bank_mask:0xf bound_ctrl:1
	v_pk_fma_f32 v[2:3], v[2:3], v[122:123], v[180:181]
	v_add_f32_dpp v198, v198, v198 quad_perm:[2,3,0,1] row_mask:0xf bank_mask:0xf bound_ctrl:1
	v_pk_fma_f32 v[6:7], v[6:7], v[122:123], v[190:191]
	v_add_f32_dpp v200, v200, v200 quad_perm:[2,3,0,1] row_mask:0xf bank_mask:0xf bound_ctrl:1
	v_pk_fma_f32 v[4:5], v[4:5], v[124:125], v[188:189]
	v_add_f32_dpp v198, v198, v198 row_half_mirror row_mask:0xf bank_mask:0xf bound_ctrl:1
	v_pk_fma_f32 v[8:9], v[8:9], v[124:125], v[192:193]
	v_add_f32_dpp v200, v200, v200 row_half_mirror row_mask:0xf bank_mask:0xf bound_ctrl:1
	s_nop 0
	v_add_f32_dpp v198, v198, v198 row_mirror row_mask:0xf bank_mask:0xf bound_ctrl:1
	s_nop 0
	v_add_f32_dpp v200, v200, v200 row_mirror row_mask:0xf bank_mask:0xf bound_ctrl:1
	v_pk_fma_f32 v[2:3], v[126:127], v[198:199], v[2:3] op_sel_hi:[1,0,1] neg_lo:[0,1,0] neg_hi:[0,1,0]
	v_pk_fma_f32 v[4:5], v[128:129], v[198:199], v[4:5] op_sel_hi:[1,0,1] neg_lo:[0,1,0] neg_hi:[0,1,0]
	v_pk_fma_f32 v[6:7], v[126:127], v[200:201], v[6:7] op_sel_hi:[1,0,1] neg_lo:[0,1,0] neg_hi:[0,1,0]
	v_pk_fma_f32 v[8:9], v[128:129], v[200:201], v[8:9] op_sel_hi:[1,0,1] neg_lo:[0,1,0] neg_hi:[0,1,0]
	v_pk_mul_f32 v[194:195], v[140:141], v[4:5]
	v_pk_mul_f32 v[196:197], v[140:141], v[8:9]
	v_pk_fma_f32 v[194:195], v[138:139], v[2:3], v[194:195]
	v_pk_fma_f32 v[196:197], v[138:139], v[6:7], v[196:197]
	v_add_f32_e32 v10, v194, v195
	v_add_f32_e32 v26, v196, v197
	s_waitcnt lgkmcnt(0)
	ds_read_b128 v[134:137], v42 offset:28416
	ds_read_b128 v[130:133], v42 offset:28160
	ds_read_b64 v[142:143], v43 offset:27648
	ds_read_b128 v[122:125], v42 offset:27648
	ds_read_b128 v[126:129], v42 offset:27904
	ds_read_b128 v[138:141], v42 offset:28672
	v_pk_mul_f32 v[176:177], v[2:3], v[166:167]
	v_pk_mul_f32 v[178:179], v[6:7], v[166:167]
	v_pk_fma_f32 v[176:177], v[4:5], v[168:169], v[176:177]
	v_pk_fma_f32 v[178:179], v[8:9], v[168:169], v[178:179]
	v_pk_mul_f32 v[180:181], v[162:163], v[174:175] op_sel_hi:[1,0]
	v_add_f32_e32 v198, v176, v177
	v_pk_mul_f32 v[190:191], v[162:163], v[174:175] op_sel:[0,1] op_sel_hi:[1,1]
	v_add_f32_e32 v200, v178, v179
	v_pk_mul_f32 v[188:189], v[164:165], v[174:175] op_sel_hi:[1,0]
	v_add_f32_dpp v198, v198, v198 quad_perm:[1,0,3,2] row_mask:0xf bank_mask:0xf bound_ctrl:1
	v_pk_mul_f32 v[192:193], v[164:165], v[174:175] op_sel:[0,1] op_sel_hi:[1,1]
	v_add_f32_dpp v200, v200, v200 quad_perm:[1,0,3,2] row_mask:0xf bank_mask:0xf bound_ctrl:1
	v_pk_fma_f32 v[2:3], v[2:3], v[154:155], v[180:181]
	v_add_f32_dpp v198, v198, v198 quad_perm:[2,3,0,1] row_mask:0xf bank_mask:0xf bound_ctrl:1
	v_pk_fma_f32 v[6:7], v[6:7], v[154:155], v[190:191]
	v_add_f32_dpp v200, v200, v200 quad_perm:[2,3,0,1] row_mask:0xf bank_mask:0xf bound_ctrl:1
	v_pk_fma_f32 v[4:5], v[4:5], v[156:157], v[188:189]
	v_add_f32_dpp v198, v198, v198 row_half_mirror row_mask:0xf bank_mask:0xf bound_ctrl:1
	v_pk_fma_f32 v[8:9], v[8:9], v[156:157], v[192:193]
	v_add_f32_dpp v200, v200, v200 row_half_mirror row_mask:0xf bank_mask:0xf bound_ctrl:1
	s_nop 0
	v_add_f32_dpp v198, v198, v198 row_mirror row_mask:0xf bank_mask:0xf bound_ctrl:1
	s_nop 0
	v_add_f32_dpp v200, v200, v200 row_mirror row_mask:0xf bank_mask:0xf bound_ctrl:1
	v_pk_fma_f32 v[2:3], v[158:159], v[198:199], v[2:3] op_sel_hi:[1,0,1] neg_lo:[0,1,0] neg_hi:[0,1,0]
	v_pk_fma_f32 v[4:5], v[160:161], v[198:199], v[4:5] op_sel_hi:[1,0,1] neg_lo:[0,1,0] neg_hi:[0,1,0]
	v_pk_fma_f32 v[6:7], v[158:159], v[200:201], v[6:7] op_sel_hi:[1,0,1] neg_lo:[0,1,0] neg_hi:[0,1,0]
	v_pk_fma_f32 v[8:9], v[160:161], v[200:201], v[8:9] op_sel_hi:[1,0,1] neg_lo:[0,1,0] neg_hi:[0,1,0]
	v_pk_mul_f32 v[194:195], v[172:173], v[4:5]
	v_pk_mul_f32 v[196:197], v[172:173], v[8:9]
	v_pk_fma_f32 v[194:195], v[170:171], v[2:3], v[194:195]
	v_pk_fma_f32 v[196:197], v[170:171], v[6:7], v[196:197]
	v_add_f32_e32 v11, v194, v195
	v_add_f32_e32 v27, v196, v197
	s_waitcnt lgkmcnt(0)
	ds_read_b128 v[166:169], v42 offset:29952
	ds_read_b128 v[162:165], v42 offset:29696
	ds_read_b64 v[174:175], v43 offset:29184
	ds_read_b128 v[154:157], v42 offset:29184
	ds_read_b128 v[158:161], v42 offset:29440
	ds_read_b128 v[170:173], v42 offset:30208
	v_pk_mul_f32 v[176:177], v[2:3], v[134:135]
	v_pk_mul_f32 v[178:179], v[6:7], v[134:135]
	v_pk_fma_f32 v[176:177], v[4:5], v[136:137], v[176:177]
	v_pk_fma_f32 v[178:179], v[8:9], v[136:137], v[178:179]
	v_pk_mul_f32 v[180:181], v[130:131], v[142:143] op_sel_hi:[1,0]
	v_add_f32_e32 v198, v176, v177
	v_pk_mul_f32 v[190:191], v[130:131], v[142:143] op_sel:[0,1] op_sel_hi:[1,1]
	v_add_f32_e32 v200, v178, v179
	v_pk_mul_f32 v[188:189], v[132:133], v[142:143] op_sel_hi:[1,0]
	v_add_f32_dpp v198, v198, v198 quad_perm:[1,0,3,2] row_mask:0xf bank_mask:0xf bound_ctrl:1
	v_pk_mul_f32 v[192:193], v[132:133], v[142:143] op_sel:[0,1] op_sel_hi:[1,1]
	v_add_f32_dpp v200, v200, v200 quad_perm:[1,0,3,2] row_mask:0xf bank_mask:0xf bound_ctrl:1
	v_pk_fma_f32 v[2:3], v[2:3], v[122:123], v[180:181]
	v_add_f32_dpp v198, v198, v198 quad_perm:[2,3,0,1] row_mask:0xf bank_mask:0xf bound_ctrl:1
	v_pk_fma_f32 v[6:7], v[6:7], v[122:123], v[190:191]
	v_add_f32_dpp v200, v200, v200 quad_perm:[2,3,0,1] row_mask:0xf bank_mask:0xf bound_ctrl:1
	v_pk_fma_f32 v[4:5], v[4:5], v[124:125], v[188:189]
	v_add_f32_dpp v198, v198, v198 row_half_mirror row_mask:0xf bank_mask:0xf bound_ctrl:1
	v_pk_fma_f32 v[8:9], v[8:9], v[124:125], v[192:193]
	v_add_f32_dpp v200, v200, v200 row_half_mirror row_mask:0xf bank_mask:0xf bound_ctrl:1
	s_nop 0
	v_add_f32_dpp v198, v198, v198 row_mirror row_mask:0xf bank_mask:0xf bound_ctrl:1
	s_nop 0
	v_add_f32_dpp v200, v200, v200 row_mirror row_mask:0xf bank_mask:0xf bound_ctrl:1
	v_pk_fma_f32 v[2:3], v[126:127], v[198:199], v[2:3] op_sel_hi:[1,0,1] neg_lo:[0,1,0] neg_hi:[0,1,0]
	v_pk_fma_f32 v[4:5], v[128:129], v[198:199], v[4:5] op_sel_hi:[1,0,1] neg_lo:[0,1,0] neg_hi:[0,1,0]
	v_pk_fma_f32 v[6:7], v[126:127], v[200:201], v[6:7] op_sel_hi:[1,0,1] neg_lo:[0,1,0] neg_hi:[0,1,0]
	v_pk_fma_f32 v[8:9], v[128:129], v[200:201], v[8:9] op_sel_hi:[1,0,1] neg_lo:[0,1,0] neg_hi:[0,1,0]
	v_pk_mul_f32 v[194:195], v[140:141], v[4:5]
	v_pk_mul_f32 v[196:197], v[140:141], v[8:9]
	v_pk_fma_f32 v[194:195], v[138:139], v[2:3], v[194:195]
	v_pk_fma_f32 v[196:197], v[138:139], v[6:7], v[196:197]
	v_add_f32_e32 v12, v194, v195
	v_add_f32_e32 v28, v196, v197
	s_waitcnt lgkmcnt(0)
	ds_read_b128 v[134:137], v42 offset:31488
	ds_read_b128 v[130:133], v42 offset:31232
	ds_read_b64 v[142:143], v43 offset:30720
	ds_read_b128 v[122:125], v42 offset:30720
	ds_read_b128 v[126:129], v42 offset:30976
	ds_read_b128 v[138:141], v42 offset:31744
	v_pk_mul_f32 v[176:177], v[2:3], v[166:167]
	v_pk_mul_f32 v[178:179], v[6:7], v[166:167]
	v_pk_fma_f32 v[176:177], v[4:5], v[168:169], v[176:177]
	v_pk_fma_f32 v[178:179], v[8:9], v[168:169], v[178:179]
	v_pk_mul_f32 v[180:181], v[162:163], v[174:175] op_sel_hi:[1,0]
	v_add_f32_e32 v198, v176, v177
	v_pk_mul_f32 v[190:191], v[162:163], v[174:175] op_sel:[0,1] op_sel_hi:[1,1]
	v_add_f32_e32 v200, v178, v179
	v_pk_mul_f32 v[188:189], v[164:165], v[174:175] op_sel_hi:[1,0]
	v_add_f32_dpp v198, v198, v198 quad_perm:[1,0,3,2] row_mask:0xf bank_mask:0xf bound_ctrl:1
	v_pk_mul_f32 v[192:193], v[164:165], v[174:175] op_sel:[0,1] op_sel_hi:[1,1]
	v_add_f32_dpp v200, v200, v200 quad_perm:[1,0,3,2] row_mask:0xf bank_mask:0xf bound_ctrl:1
	v_pk_fma_f32 v[2:3], v[2:3], v[154:155], v[180:181]
	v_add_f32_dpp v198, v198, v198 quad_perm:[2,3,0,1] row_mask:0xf bank_mask:0xf bound_ctrl:1
	v_pk_fma_f32 v[6:7], v[6:7], v[154:155], v[190:191]
	v_add_f32_dpp v200, v200, v200 quad_perm:[2,3,0,1] row_mask:0xf bank_mask:0xf bound_ctrl:1
	v_pk_fma_f32 v[4:5], v[4:5], v[156:157], v[188:189]
	v_add_f32_dpp v198, v198, v198 row_half_mirror row_mask:0xf bank_mask:0xf bound_ctrl:1
	v_pk_fma_f32 v[8:9], v[8:9], v[156:157], v[192:193]
	v_add_f32_dpp v200, v200, v200 row_half_mirror row_mask:0xf bank_mask:0xf bound_ctrl:1
	s_nop 0
	v_add_f32_dpp v198, v198, v198 row_mirror row_mask:0xf bank_mask:0xf bound_ctrl:1
	s_nop 0
	v_add_f32_dpp v200, v200, v200 row_mirror row_mask:0xf bank_mask:0xf bound_ctrl:1
	v_pk_fma_f32 v[2:3], v[158:159], v[198:199], v[2:3] op_sel_hi:[1,0,1] neg_lo:[0,1,0] neg_hi:[0,1,0]
	v_pk_fma_f32 v[4:5], v[160:161], v[198:199], v[4:5] op_sel_hi:[1,0,1] neg_lo:[0,1,0] neg_hi:[0,1,0]
	v_pk_fma_f32 v[6:7], v[158:159], v[200:201], v[6:7] op_sel_hi:[1,0,1] neg_lo:[0,1,0] neg_hi:[0,1,0]
	v_pk_fma_f32 v[8:9], v[160:161], v[200:201], v[8:9] op_sel_hi:[1,0,1] neg_lo:[0,1,0] neg_hi:[0,1,0]
	v_pk_mul_f32 v[194:195], v[172:173], v[4:5]
	v_pk_mul_f32 v[196:197], v[172:173], v[8:9]
	v_pk_fma_f32 v[194:195], v[170:171], v[2:3], v[194:195]
	v_pk_fma_f32 v[196:197], v[170:171], v[6:7], v[196:197]
	v_add_f32_e32 v13, v194, v195
	v_add_f32_e32 v29, v196, v197
	s_waitcnt lgkmcnt(0)
	ds_read_b128 v[166:169], v42 offset:33024
	ds_read_b128 v[162:165], v42 offset:32768
	ds_read_b64 v[174:175], v43 offset:32256
	ds_read_b128 v[154:157], v42 offset:32256
	ds_read_b128 v[158:161], v42 offset:32512
	ds_read_b128 v[170:173], v42 offset:33280
	v_pk_mul_f32 v[176:177], v[2:3], v[134:135]
	v_pk_mul_f32 v[178:179], v[6:7], v[134:135]
	v_pk_fma_f32 v[176:177], v[4:5], v[136:137], v[176:177]
	v_pk_fma_f32 v[178:179], v[8:9], v[136:137], v[178:179]
	v_pk_mul_f32 v[180:181], v[130:131], v[142:143] op_sel_hi:[1,0]
	v_add_f32_e32 v198, v176, v177
	v_pk_mul_f32 v[190:191], v[130:131], v[142:143] op_sel:[0,1] op_sel_hi:[1,1]
	v_add_f32_e32 v200, v178, v179
	v_pk_mul_f32 v[188:189], v[132:133], v[142:143] op_sel_hi:[1,0]
	v_add_f32_dpp v198, v198, v198 quad_perm:[1,0,3,2] row_mask:0xf bank_mask:0xf bound_ctrl:1
	v_pk_mul_f32 v[192:193], v[132:133], v[142:143] op_sel:[0,1] op_sel_hi:[1,1]
	v_add_f32_dpp v200, v200, v200 quad_perm:[1,0,3,2] row_mask:0xf bank_mask:0xf bound_ctrl:1
	v_pk_fma_f32 v[2:3], v[2:3], v[122:123], v[180:181]
	v_add_f32_dpp v198, v198, v198 quad_perm:[2,3,0,1] row_mask:0xf bank_mask:0xf bound_ctrl:1
	v_pk_fma_f32 v[6:7], v[6:7], v[122:123], v[190:191]
	v_add_f32_dpp v200, v200, v200 quad_perm:[2,3,0,1] row_mask:0xf bank_mask:0xf bound_ctrl:1
	v_pk_fma_f32 v[4:5], v[4:5], v[124:125], v[188:189]
	v_add_f32_dpp v198, v198, v198 row_half_mirror row_mask:0xf bank_mask:0xf bound_ctrl:1
	v_pk_fma_f32 v[8:9], v[8:9], v[124:125], v[192:193]
	v_add_f32_dpp v200, v200, v200 row_half_mirror row_mask:0xf bank_mask:0xf bound_ctrl:1
	s_nop 0
	v_add_f32_dpp v198, v198, v198 row_mirror row_mask:0xf bank_mask:0xf bound_ctrl:1
	s_nop 0
	v_add_f32_dpp v200, v200, v200 row_mirror row_mask:0xf bank_mask:0xf bound_ctrl:1
	v_pk_fma_f32 v[2:3], v[126:127], v[198:199], v[2:3] op_sel_hi:[1,0,1] neg_lo:[0,1,0] neg_hi:[0,1,0]
	v_pk_fma_f32 v[4:5], v[128:129], v[198:199], v[4:5] op_sel_hi:[1,0,1] neg_lo:[0,1,0] neg_hi:[0,1,0]
	v_pk_fma_f32 v[6:7], v[126:127], v[200:201], v[6:7] op_sel_hi:[1,0,1] neg_lo:[0,1,0] neg_hi:[0,1,0]
	v_pk_fma_f32 v[8:9], v[128:129], v[200:201], v[8:9] op_sel_hi:[1,0,1] neg_lo:[0,1,0] neg_hi:[0,1,0]
	v_pk_mul_f32 v[194:195], v[140:141], v[4:5]
	v_pk_mul_f32 v[196:197], v[140:141], v[8:9]
	v_pk_fma_f32 v[194:195], v[138:139], v[2:3], v[194:195]
	v_pk_fma_f32 v[196:197], v[138:139], v[6:7], v[196:197]
	v_add_f32_e32 v14, v194, v195
	v_add_f32_e32 v30, v196, v197
	s_waitcnt lgkmcnt(0)
	ds_read_b128 v[134:137], v42 offset:34560
	ds_read_b128 v[130:133], v42 offset:34304
	ds_read_b64 v[142:143], v43 offset:33792
	ds_read_b128 v[122:125], v42 offset:33792
	ds_read_b128 v[126:129], v42 offset:34048
	ds_read_b128 v[138:141], v42 offset:34816
	v_pk_mul_f32 v[176:177], v[2:3], v[166:167]
	v_pk_mul_f32 v[178:179], v[6:7], v[166:167]
	v_pk_fma_f32 v[176:177], v[4:5], v[168:169], v[176:177]
	v_pk_fma_f32 v[178:179], v[8:9], v[168:169], v[178:179]
	v_pk_mul_f32 v[180:181], v[162:163], v[174:175] op_sel_hi:[1,0]
	v_add_f32_e32 v198, v176, v177
	v_pk_mul_f32 v[190:191], v[162:163], v[174:175] op_sel:[0,1] op_sel_hi:[1,1]
	v_add_f32_e32 v200, v178, v179
	v_pk_mul_f32 v[188:189], v[164:165], v[174:175] op_sel_hi:[1,0]
	v_add_f32_dpp v198, v198, v198 quad_perm:[1,0,3,2] row_mask:0xf bank_mask:0xf bound_ctrl:1
	v_pk_mul_f32 v[192:193], v[164:165], v[174:175] op_sel:[0,1] op_sel_hi:[1,1]
	v_add_f32_dpp v200, v200, v200 quad_perm:[1,0,3,2] row_mask:0xf bank_mask:0xf bound_ctrl:1
	v_pk_fma_f32 v[2:3], v[2:3], v[154:155], v[180:181]
	v_add_f32_dpp v198, v198, v198 quad_perm:[2,3,0,1] row_mask:0xf bank_mask:0xf bound_ctrl:1
	v_pk_fma_f32 v[6:7], v[6:7], v[154:155], v[190:191]
	v_add_f32_dpp v200, v200, v200 quad_perm:[2,3,0,1] row_mask:0xf bank_mask:0xf bound_ctrl:1
	v_pk_fma_f32 v[4:5], v[4:5], v[156:157], v[188:189]
	v_add_f32_dpp v198, v198, v198 row_half_mirror row_mask:0xf bank_mask:0xf bound_ctrl:1
	v_pk_fma_f32 v[8:9], v[8:9], v[156:157], v[192:193]
	v_add_f32_dpp v200, v200, v200 row_half_mirror row_mask:0xf bank_mask:0xf bound_ctrl:1
	s_nop 0
	v_add_f32_dpp v198, v198, v198 row_mirror row_mask:0xf bank_mask:0xf bound_ctrl:1
	s_nop 0
	v_add_f32_dpp v200, v200, v200 row_mirror row_mask:0xf bank_mask:0xf bound_ctrl:1
	v_pk_fma_f32 v[2:3], v[158:159], v[198:199], v[2:3] op_sel_hi:[1,0,1] neg_lo:[0,1,0] neg_hi:[0,1,0]
	v_pk_fma_f32 v[4:5], v[160:161], v[198:199], v[4:5] op_sel_hi:[1,0,1] neg_lo:[0,1,0] neg_hi:[0,1,0]
	v_pk_fma_f32 v[6:7], v[158:159], v[200:201], v[6:7] op_sel_hi:[1,0,1] neg_lo:[0,1,0] neg_hi:[0,1,0]
	v_pk_fma_f32 v[8:9], v[160:161], v[200:201], v[8:9] op_sel_hi:[1,0,1] neg_lo:[0,1,0] neg_hi:[0,1,0]
	v_pk_mul_f32 v[194:195], v[172:173], v[4:5]
	v_pk_mul_f32 v[196:197], v[172:173], v[8:9]
	v_pk_fma_f32 v[194:195], v[170:171], v[2:3], v[194:195]
	v_pk_fma_f32 v[196:197], v[170:171], v[6:7], v[196:197]
	v_add_f32_e32 v15, v194, v195
	v_add_f32_e32 v31, v196, v197
	s_waitcnt lgkmcnt(0)
	ds_read_b128 v[166:169], v42 offset:36096
	ds_read_b128 v[162:165], v42 offset:35840
	ds_read_b64 v[174:175], v43 offset:35328
	ds_read_b128 v[154:157], v42 offset:35328
	ds_read_b128 v[158:161], v42 offset:35584
	ds_read_b128 v[170:173], v42 offset:36352
	v_pk_mul_f32 v[176:177], v[2:3], v[134:135]
	v_pk_mul_f32 v[178:179], v[6:7], v[134:135]
	v_pk_fma_f32 v[176:177], v[4:5], v[136:137], v[176:177]
	v_pk_fma_f32 v[178:179], v[8:9], v[136:137], v[178:179]
	v_pk_mul_f32 v[180:181], v[130:131], v[142:143] op_sel_hi:[1,0]
	v_add_f32_e32 v198, v176, v177
	v_pk_mul_f32 v[190:191], v[130:131], v[142:143] op_sel:[0,1] op_sel_hi:[1,1]
	v_add_f32_e32 v200, v178, v179
	v_pk_mul_f32 v[188:189], v[132:133], v[142:143] op_sel_hi:[1,0]
	v_add_f32_dpp v198, v198, v198 quad_perm:[1,0,3,2] row_mask:0xf bank_mask:0xf bound_ctrl:1
	v_pk_mul_f32 v[192:193], v[132:133], v[142:143] op_sel:[0,1] op_sel_hi:[1,1]
	v_add_f32_dpp v200, v200, v200 quad_perm:[1,0,3,2] row_mask:0xf bank_mask:0xf bound_ctrl:1
	v_pk_fma_f32 v[2:3], v[2:3], v[122:123], v[180:181]
	v_add_f32_dpp v198, v198, v198 quad_perm:[2,3,0,1] row_mask:0xf bank_mask:0xf bound_ctrl:1
	v_pk_fma_f32 v[6:7], v[6:7], v[122:123], v[190:191]
	v_add_f32_dpp v200, v200, v200 quad_perm:[2,3,0,1] row_mask:0xf bank_mask:0xf bound_ctrl:1
	v_pk_fma_f32 v[4:5], v[4:5], v[124:125], v[188:189]
	v_add_f32_dpp v198, v198, v198 row_half_mirror row_mask:0xf bank_mask:0xf bound_ctrl:1
	v_pk_fma_f32 v[8:9], v[8:9], v[124:125], v[192:193]
	v_add_f32_dpp v200, v200, v200 row_half_mirror row_mask:0xf bank_mask:0xf bound_ctrl:1
	s_nop 0
	v_add_f32_dpp v198, v198, v198 row_mirror row_mask:0xf bank_mask:0xf bound_ctrl:1
	s_nop 0
	v_add_f32_dpp v200, v200, v200 row_mirror row_mask:0xf bank_mask:0xf bound_ctrl:1
	v_pk_fma_f32 v[2:3], v[126:127], v[198:199], v[2:3] op_sel_hi:[1,0,1] neg_lo:[0,1,0] neg_hi:[0,1,0]
	v_pk_fma_f32 v[4:5], v[128:129], v[198:199], v[4:5] op_sel_hi:[1,0,1] neg_lo:[0,1,0] neg_hi:[0,1,0]
	v_pk_fma_f32 v[6:7], v[126:127], v[200:201], v[6:7] op_sel_hi:[1,0,1] neg_lo:[0,1,0] neg_hi:[0,1,0]
	v_pk_fma_f32 v[8:9], v[128:129], v[200:201], v[8:9] op_sel_hi:[1,0,1] neg_lo:[0,1,0] neg_hi:[0,1,0]
	v_pk_mul_f32 v[194:195], v[140:141], v[4:5]
	v_pk_mul_f32 v[196:197], v[140:141], v[8:9]
	v_pk_fma_f32 v[194:195], v[138:139], v[2:3], v[194:195]
	v_pk_fma_f32 v[196:197], v[138:139], v[6:7], v[196:197]
	v_add_f32_e32 v16, v194, v195
	v_add_f32_e32 v32, v196, v197
	s_waitcnt lgkmcnt(0)
	ds_read_b128 v[134:137], v42 offset:37632
	ds_read_b128 v[130:133], v42 offset:37376
	ds_read_b64 v[142:143], v43 offset:36864
	ds_read_b128 v[122:125], v42 offset:36864
	ds_read_b128 v[126:129], v42 offset:37120
	ds_read_b128 v[138:141], v42 offset:37888
	v_pk_mul_f32 v[176:177], v[2:3], v[166:167]
	v_pk_mul_f32 v[178:179], v[6:7], v[166:167]
	v_pk_fma_f32 v[176:177], v[4:5], v[168:169], v[176:177]
	v_pk_fma_f32 v[178:179], v[8:9], v[168:169], v[178:179]
	v_pk_mul_f32 v[180:181], v[162:163], v[174:175] op_sel_hi:[1,0]
	v_add_f32_e32 v198, v176, v177
	v_pk_mul_f32 v[190:191], v[162:163], v[174:175] op_sel:[0,1] op_sel_hi:[1,1]
	v_add_f32_e32 v200, v178, v179
	v_pk_mul_f32 v[188:189], v[164:165], v[174:175] op_sel_hi:[1,0]
	v_add_f32_dpp v198, v198, v198 quad_perm:[1,0,3,2] row_mask:0xf bank_mask:0xf bound_ctrl:1
	v_pk_mul_f32 v[192:193], v[164:165], v[174:175] op_sel:[0,1] op_sel_hi:[1,1]
	v_add_f32_dpp v200, v200, v200 quad_perm:[1,0,3,2] row_mask:0xf bank_mask:0xf bound_ctrl:1
	v_pk_fma_f32 v[2:3], v[2:3], v[154:155], v[180:181]
	v_add_f32_dpp v198, v198, v198 quad_perm:[2,3,0,1] row_mask:0xf bank_mask:0xf bound_ctrl:1
	v_pk_fma_f32 v[6:7], v[6:7], v[154:155], v[190:191]
	v_add_f32_dpp v200, v200, v200 quad_perm:[2,3,0,1] row_mask:0xf bank_mask:0xf bound_ctrl:1
	v_pk_fma_f32 v[4:5], v[4:5], v[156:157], v[188:189]
	v_add_f32_dpp v198, v198, v198 row_half_mirror row_mask:0xf bank_mask:0xf bound_ctrl:1
	v_pk_fma_f32 v[8:9], v[8:9], v[156:157], v[192:193]
	v_add_f32_dpp v200, v200, v200 row_half_mirror row_mask:0xf bank_mask:0xf bound_ctrl:1
	s_nop 0
	v_add_f32_dpp v198, v198, v198 row_mirror row_mask:0xf bank_mask:0xf bound_ctrl:1
	s_nop 0
	v_add_f32_dpp v200, v200, v200 row_mirror row_mask:0xf bank_mask:0xf bound_ctrl:1
	v_pk_fma_f32 v[2:3], v[158:159], v[198:199], v[2:3] op_sel_hi:[1,0,1] neg_lo:[0,1,0] neg_hi:[0,1,0]
	v_pk_fma_f32 v[4:5], v[160:161], v[198:199], v[4:5] op_sel_hi:[1,0,1] neg_lo:[0,1,0] neg_hi:[0,1,0]
	v_pk_fma_f32 v[6:7], v[158:159], v[200:201], v[6:7] op_sel_hi:[1,0,1] neg_lo:[0,1,0] neg_hi:[0,1,0]
	v_pk_fma_f32 v[8:9], v[160:161], v[200:201], v[8:9] op_sel_hi:[1,0,1] neg_lo:[0,1,0] neg_hi:[0,1,0]
	v_pk_mul_f32 v[194:195], v[172:173], v[4:5]
	v_pk_mul_f32 v[196:197], v[172:173], v[8:9]
	v_pk_fma_f32 v[194:195], v[170:171], v[2:3], v[194:195]
	v_pk_fma_f32 v[196:197], v[170:171], v[6:7], v[196:197]
	v_add_f32_e32 v17, v194, v195
	v_add_f32_e32 v33, v196, v197
	s_waitcnt lgkmcnt(0)
	ds_read_b128 v[166:169], v42 offset:39168
	ds_read_b128 v[162:165], v42 offset:38912
	ds_read_b64 v[174:175], v43 offset:38400
	ds_read_b128 v[154:157], v42 offset:38400
	ds_read_b128 v[158:161], v42 offset:38656
	ds_read_b128 v[170:173], v42 offset:39424
	v_pk_mul_f32 v[176:177], v[2:3], v[134:135]
	v_pk_mul_f32 v[178:179], v[6:7], v[134:135]
	v_pk_fma_f32 v[176:177], v[4:5], v[136:137], v[176:177]
	v_pk_fma_f32 v[178:179], v[8:9], v[136:137], v[178:179]
	v_pk_mul_f32 v[180:181], v[130:131], v[142:143] op_sel_hi:[1,0]
	v_add_f32_e32 v198, v176, v177
	v_pk_mul_f32 v[190:191], v[130:131], v[142:143] op_sel:[0,1] op_sel_hi:[1,1]
	v_add_f32_e32 v200, v178, v179
	v_pk_mul_f32 v[188:189], v[132:133], v[142:143] op_sel_hi:[1,0]
	v_add_f32_dpp v198, v198, v198 quad_perm:[1,0,3,2] row_mask:0xf bank_mask:0xf bound_ctrl:1
	v_pk_mul_f32 v[192:193], v[132:133], v[142:143] op_sel:[0,1] op_sel_hi:[1,1]
	v_add_f32_dpp v200, v200, v200 quad_perm:[1,0,3,2] row_mask:0xf bank_mask:0xf bound_ctrl:1
	v_pk_fma_f32 v[2:3], v[2:3], v[122:123], v[180:181]
	v_add_f32_dpp v198, v198, v198 quad_perm:[2,3,0,1] row_mask:0xf bank_mask:0xf bound_ctrl:1
	v_pk_fma_f32 v[6:7], v[6:7], v[122:123], v[190:191]
	v_add_f32_dpp v200, v200, v200 quad_perm:[2,3,0,1] row_mask:0xf bank_mask:0xf bound_ctrl:1
	v_pk_fma_f32 v[4:5], v[4:5], v[124:125], v[188:189]
	v_add_f32_dpp v198, v198, v198 row_half_mirror row_mask:0xf bank_mask:0xf bound_ctrl:1
	v_pk_fma_f32 v[8:9], v[8:9], v[124:125], v[192:193]
	v_add_f32_dpp v200, v200, v200 row_half_mirror row_mask:0xf bank_mask:0xf bound_ctrl:1
	s_nop 0
	v_add_f32_dpp v198, v198, v198 row_mirror row_mask:0xf bank_mask:0xf bound_ctrl:1
	s_nop 0
	v_add_f32_dpp v200, v200, v200 row_mirror row_mask:0xf bank_mask:0xf bound_ctrl:1
	v_pk_fma_f32 v[2:3], v[126:127], v[198:199], v[2:3] op_sel_hi:[1,0,1] neg_lo:[0,1,0] neg_hi:[0,1,0]
	v_pk_fma_f32 v[4:5], v[128:129], v[198:199], v[4:5] op_sel_hi:[1,0,1] neg_lo:[0,1,0] neg_hi:[0,1,0]
	v_pk_fma_f32 v[6:7], v[126:127], v[200:201], v[6:7] op_sel_hi:[1,0,1] neg_lo:[0,1,0] neg_hi:[0,1,0]
	v_pk_fma_f32 v[8:9], v[128:129], v[200:201], v[8:9] op_sel_hi:[1,0,1] neg_lo:[0,1,0] neg_hi:[0,1,0]
	v_pk_mul_f32 v[194:195], v[140:141], v[4:5]
	v_pk_mul_f32 v[196:197], v[140:141], v[8:9]
	v_pk_fma_f32 v[194:195], v[138:139], v[2:3], v[194:195]
	v_pk_fma_f32 v[196:197], v[138:139], v[6:7], v[196:197]
	v_add_f32_e32 v18, v194, v195
	v_add_f32_e32 v34, v196, v197
	s_waitcnt lgkmcnt(0)
	ds_read_b128 v[134:137], v42 offset:40704
	ds_read_b128 v[130:133], v42 offset:40448
	ds_read_b64 v[142:143], v43 offset:39936
	ds_read_b128 v[122:125], v42 offset:39936
	ds_read_b128 v[126:129], v42 offset:40192
	ds_read_b128 v[138:141], v42 offset:40960
	v_pk_mul_f32 v[176:177], v[2:3], v[166:167]
	v_pk_mul_f32 v[178:179], v[6:7], v[166:167]
	v_pk_fma_f32 v[176:177], v[4:5], v[168:169], v[176:177]
	v_pk_fma_f32 v[178:179], v[8:9], v[168:169], v[178:179]
	v_pk_mul_f32 v[180:181], v[162:163], v[174:175] op_sel_hi:[1,0]
	v_add_f32_e32 v198, v176, v177
	v_pk_mul_f32 v[190:191], v[162:163], v[174:175] op_sel:[0,1] op_sel_hi:[1,1]
	v_add_f32_e32 v200, v178, v179
	v_pk_mul_f32 v[188:189], v[164:165], v[174:175] op_sel_hi:[1,0]
	v_add_f32_dpp v198, v198, v198 quad_perm:[1,0,3,2] row_mask:0xf bank_mask:0xf bound_ctrl:1
	v_pk_mul_f32 v[192:193], v[164:165], v[174:175] op_sel:[0,1] op_sel_hi:[1,1]
	v_add_f32_dpp v200, v200, v200 quad_perm:[1,0,3,2] row_mask:0xf bank_mask:0xf bound_ctrl:1
	v_pk_fma_f32 v[2:3], v[2:3], v[154:155], v[180:181]
	v_add_f32_dpp v198, v198, v198 quad_perm:[2,3,0,1] row_mask:0xf bank_mask:0xf bound_ctrl:1
	v_pk_fma_f32 v[6:7], v[6:7], v[154:155], v[190:191]
	v_add_f32_dpp v200, v200, v200 quad_perm:[2,3,0,1] row_mask:0xf bank_mask:0xf bound_ctrl:1
	v_pk_fma_f32 v[4:5], v[4:5], v[156:157], v[188:189]
	v_add_f32_dpp v198, v198, v198 row_half_mirror row_mask:0xf bank_mask:0xf bound_ctrl:1
	v_pk_fma_f32 v[8:9], v[8:9], v[156:157], v[192:193]
	v_add_f32_dpp v200, v200, v200 row_half_mirror row_mask:0xf bank_mask:0xf bound_ctrl:1
	s_nop 0
	v_add_f32_dpp v198, v198, v198 row_mirror row_mask:0xf bank_mask:0xf bound_ctrl:1
	s_nop 0
	v_add_f32_dpp v200, v200, v200 row_mirror row_mask:0xf bank_mask:0xf bound_ctrl:1
	v_pk_fma_f32 v[2:3], v[158:159], v[198:199], v[2:3] op_sel_hi:[1,0,1] neg_lo:[0,1,0] neg_hi:[0,1,0]
	v_pk_fma_f32 v[4:5], v[160:161], v[198:199], v[4:5] op_sel_hi:[1,0,1] neg_lo:[0,1,0] neg_hi:[0,1,0]
	v_pk_fma_f32 v[6:7], v[158:159], v[200:201], v[6:7] op_sel_hi:[1,0,1] neg_lo:[0,1,0] neg_hi:[0,1,0]
	v_pk_fma_f32 v[8:9], v[160:161], v[200:201], v[8:9] op_sel_hi:[1,0,1] neg_lo:[0,1,0] neg_hi:[0,1,0]
	v_pk_mul_f32 v[194:195], v[172:173], v[4:5]
	v_pk_mul_f32 v[196:197], v[172:173], v[8:9]
	v_pk_fma_f32 v[194:195], v[170:171], v[2:3], v[194:195]
	v_pk_fma_f32 v[196:197], v[170:171], v[6:7], v[196:197]
	v_add_f32_e32 v19, v194, v195
	v_add_f32_e32 v35, v196, v197
	s_waitcnt lgkmcnt(0)
	ds_read_b128 v[166:169], v42 offset:42240
	ds_read_b128 v[162:165], v42 offset:41984
	ds_read_b64 v[174:175], v43 offset:41472
	ds_read_b128 v[154:157], v42 offset:41472
	ds_read_b128 v[158:161], v42 offset:41728
	ds_read_b128 v[170:173], v42 offset:42496
	v_pk_mul_f32 v[176:177], v[2:3], v[134:135]
	v_pk_mul_f32 v[178:179], v[6:7], v[134:135]
	v_pk_fma_f32 v[176:177], v[4:5], v[136:137], v[176:177]
	v_pk_fma_f32 v[178:179], v[8:9], v[136:137], v[178:179]
	v_pk_mul_f32 v[180:181], v[130:131], v[142:143] op_sel_hi:[1,0]
	v_add_f32_e32 v198, v176, v177
	v_pk_mul_f32 v[190:191], v[130:131], v[142:143] op_sel:[0,1] op_sel_hi:[1,1]
	v_add_f32_e32 v200, v178, v179
	v_pk_mul_f32 v[188:189], v[132:133], v[142:143] op_sel_hi:[1,0]
	v_add_f32_dpp v198, v198, v198 quad_perm:[1,0,3,2] row_mask:0xf bank_mask:0xf bound_ctrl:1
	v_pk_mul_f32 v[192:193], v[132:133], v[142:143] op_sel:[0,1] op_sel_hi:[1,1]
	v_add_f32_dpp v200, v200, v200 quad_perm:[1,0,3,2] row_mask:0xf bank_mask:0xf bound_ctrl:1
	v_pk_fma_f32 v[2:3], v[2:3], v[122:123], v[180:181]
	v_add_f32_dpp v198, v198, v198 quad_perm:[2,3,0,1] row_mask:0xf bank_mask:0xf bound_ctrl:1
	v_pk_fma_f32 v[6:7], v[6:7], v[122:123], v[190:191]
	v_add_f32_dpp v200, v200, v200 quad_perm:[2,3,0,1] row_mask:0xf bank_mask:0xf bound_ctrl:1
	v_pk_fma_f32 v[4:5], v[4:5], v[124:125], v[188:189]
	v_add_f32_dpp v198, v198, v198 row_half_mirror row_mask:0xf bank_mask:0xf bound_ctrl:1
	v_pk_fma_f32 v[8:9], v[8:9], v[124:125], v[192:193]
	v_add_f32_dpp v200, v200, v200 row_half_mirror row_mask:0xf bank_mask:0xf bound_ctrl:1
	s_nop 0
	v_add_f32_dpp v198, v198, v198 row_mirror row_mask:0xf bank_mask:0xf bound_ctrl:1
	s_nop 0
	v_add_f32_dpp v200, v200, v200 row_mirror row_mask:0xf bank_mask:0xf bound_ctrl:1
	v_pk_fma_f32 v[2:3], v[126:127], v[198:199], v[2:3] op_sel_hi:[1,0,1] neg_lo:[0,1,0] neg_hi:[0,1,0]
	v_pk_fma_f32 v[4:5], v[128:129], v[198:199], v[4:5] op_sel_hi:[1,0,1] neg_lo:[0,1,0] neg_hi:[0,1,0]
	v_pk_fma_f32 v[6:7], v[126:127], v[200:201], v[6:7] op_sel_hi:[1,0,1] neg_lo:[0,1,0] neg_hi:[0,1,0]
	v_pk_fma_f32 v[8:9], v[128:129], v[200:201], v[8:9] op_sel_hi:[1,0,1] neg_lo:[0,1,0] neg_hi:[0,1,0]
	v_pk_mul_f32 v[194:195], v[140:141], v[4:5]
	v_pk_mul_f32 v[196:197], v[140:141], v[8:9]
	v_pk_fma_f32 v[194:195], v[138:139], v[2:3], v[194:195]
	v_pk_fma_f32 v[196:197], v[138:139], v[6:7], v[196:197]
	v_add_f32_e32 v20, v194, v195
	v_add_f32_e32 v36, v196, v197
	s_waitcnt lgkmcnt(0)
	ds_read_b128 v[134:137], v42 offset:43776
	ds_read_b128 v[130:133], v42 offset:43520
	ds_read_b64 v[142:143], v43 offset:43008
	ds_read_b128 v[122:125], v42 offset:43008
	ds_read_b128 v[126:129], v42 offset:43264
	ds_read_b128 v[138:141], v42 offset:44032
	v_pk_mul_f32 v[176:177], v[2:3], v[166:167]
	v_pk_mul_f32 v[178:179], v[6:7], v[166:167]
	v_pk_fma_f32 v[176:177], v[4:5], v[168:169], v[176:177]
	v_pk_fma_f32 v[178:179], v[8:9], v[168:169], v[178:179]
	v_pk_mul_f32 v[180:181], v[162:163], v[174:175] op_sel_hi:[1,0]
	v_add_f32_e32 v198, v176, v177
	v_pk_mul_f32 v[190:191], v[162:163], v[174:175] op_sel:[0,1] op_sel_hi:[1,1]
	v_add_f32_e32 v200, v178, v179
	v_pk_mul_f32 v[188:189], v[164:165], v[174:175] op_sel_hi:[1,0]
	v_add_f32_dpp v198, v198, v198 quad_perm:[1,0,3,2] row_mask:0xf bank_mask:0xf bound_ctrl:1
	v_pk_mul_f32 v[192:193], v[164:165], v[174:175] op_sel:[0,1] op_sel_hi:[1,1]
	v_add_f32_dpp v200, v200, v200 quad_perm:[1,0,3,2] row_mask:0xf bank_mask:0xf bound_ctrl:1
	v_pk_fma_f32 v[2:3], v[2:3], v[154:155], v[180:181]
	v_add_f32_dpp v198, v198, v198 quad_perm:[2,3,0,1] row_mask:0xf bank_mask:0xf bound_ctrl:1
	v_pk_fma_f32 v[6:7], v[6:7], v[154:155], v[190:191]
	v_add_f32_dpp v200, v200, v200 quad_perm:[2,3,0,1] row_mask:0xf bank_mask:0xf bound_ctrl:1
	v_pk_fma_f32 v[4:5], v[4:5], v[156:157], v[188:189]
	v_add_f32_dpp v198, v198, v198 row_half_mirror row_mask:0xf bank_mask:0xf bound_ctrl:1
	v_pk_fma_f32 v[8:9], v[8:9], v[156:157], v[192:193]
	v_add_f32_dpp v200, v200, v200 row_half_mirror row_mask:0xf bank_mask:0xf bound_ctrl:1
	s_nop 0
	v_add_f32_dpp v198, v198, v198 row_mirror row_mask:0xf bank_mask:0xf bound_ctrl:1
	s_nop 0
	v_add_f32_dpp v200, v200, v200 row_mirror row_mask:0xf bank_mask:0xf bound_ctrl:1
	v_pk_fma_f32 v[2:3], v[158:159], v[198:199], v[2:3] op_sel_hi:[1,0,1] neg_lo:[0,1,0] neg_hi:[0,1,0]
	v_pk_fma_f32 v[4:5], v[160:161], v[198:199], v[4:5] op_sel_hi:[1,0,1] neg_lo:[0,1,0] neg_hi:[0,1,0]
	v_pk_fma_f32 v[6:7], v[158:159], v[200:201], v[6:7] op_sel_hi:[1,0,1] neg_lo:[0,1,0] neg_hi:[0,1,0]
	v_pk_fma_f32 v[8:9], v[160:161], v[200:201], v[8:9] op_sel_hi:[1,0,1] neg_lo:[0,1,0] neg_hi:[0,1,0]
	v_pk_mul_f32 v[194:195], v[172:173], v[4:5]
	v_pk_mul_f32 v[196:197], v[172:173], v[8:9]
	v_pk_fma_f32 v[194:195], v[170:171], v[2:3], v[194:195]
	v_pk_fma_f32 v[196:197], v[170:171], v[6:7], v[196:197]
	v_add_f32_e32 v21, v194, v195
	v_add_f32_e32 v37, v196, v197
	s_waitcnt lgkmcnt(0)
	ds_read_b128 v[166:169], v42 offset:45312
	ds_read_b128 v[162:165], v42 offset:45056
	ds_read_b64 v[174:175], v43 offset:44544
	ds_read_b128 v[154:157], v42 offset:44544
	ds_read_b128 v[158:161], v42 offset:44800
	ds_read_b128 v[170:173], v42 offset:45568
	v_pk_mul_f32 v[176:177], v[2:3], v[134:135]
	v_pk_mul_f32 v[178:179], v[6:7], v[134:135]
	v_pk_fma_f32 v[176:177], v[4:5], v[136:137], v[176:177]
	v_pk_fma_f32 v[178:179], v[8:9], v[136:137], v[178:179]
	v_pk_mul_f32 v[180:181], v[130:131], v[142:143] op_sel_hi:[1,0]
	v_add_f32_e32 v198, v176, v177
	v_pk_mul_f32 v[190:191], v[130:131], v[142:143] op_sel:[0,1] op_sel_hi:[1,1]
	v_add_f32_e32 v200, v178, v179
	v_pk_mul_f32 v[188:189], v[132:133], v[142:143] op_sel_hi:[1,0]
	v_add_f32_dpp v198, v198, v198 quad_perm:[1,0,3,2] row_mask:0xf bank_mask:0xf bound_ctrl:1
	v_pk_mul_f32 v[192:193], v[132:133], v[142:143] op_sel:[0,1] op_sel_hi:[1,1]
	v_add_f32_dpp v200, v200, v200 quad_perm:[1,0,3,2] row_mask:0xf bank_mask:0xf bound_ctrl:1
	v_pk_fma_f32 v[2:3], v[2:3], v[122:123], v[180:181]
	v_add_f32_dpp v198, v198, v198 quad_perm:[2,3,0,1] row_mask:0xf bank_mask:0xf bound_ctrl:1
	v_pk_fma_f32 v[6:7], v[6:7], v[122:123], v[190:191]
	v_add_f32_dpp v200, v200, v200 quad_perm:[2,3,0,1] row_mask:0xf bank_mask:0xf bound_ctrl:1
	v_pk_fma_f32 v[4:5], v[4:5], v[124:125], v[188:189]
	v_add_f32_dpp v198, v198, v198 row_half_mirror row_mask:0xf bank_mask:0xf bound_ctrl:1
	v_pk_fma_f32 v[8:9], v[8:9], v[124:125], v[192:193]
	v_add_f32_dpp v200, v200, v200 row_half_mirror row_mask:0xf bank_mask:0xf bound_ctrl:1
	s_nop 0
	v_add_f32_dpp v198, v198, v198 row_mirror row_mask:0xf bank_mask:0xf bound_ctrl:1
	s_nop 0
	v_add_f32_dpp v200, v200, v200 row_mirror row_mask:0xf bank_mask:0xf bound_ctrl:1
	v_pk_fma_f32 v[2:3], v[126:127], v[198:199], v[2:3] op_sel_hi:[1,0,1] neg_lo:[0,1,0] neg_hi:[0,1,0]
	v_pk_fma_f32 v[4:5], v[128:129], v[198:199], v[4:5] op_sel_hi:[1,0,1] neg_lo:[0,1,0] neg_hi:[0,1,0]
	v_pk_fma_f32 v[6:7], v[126:127], v[200:201], v[6:7] op_sel_hi:[1,0,1] neg_lo:[0,1,0] neg_hi:[0,1,0]
	v_pk_fma_f32 v[8:9], v[128:129], v[200:201], v[8:9] op_sel_hi:[1,0,1] neg_lo:[0,1,0] neg_hi:[0,1,0]
	v_pk_mul_f32 v[194:195], v[140:141], v[4:5]
	v_pk_mul_f32 v[196:197], v[140:141], v[8:9]
	v_pk_fma_f32 v[194:195], v[138:139], v[2:3], v[194:195]
	v_pk_fma_f32 v[196:197], v[138:139], v[6:7], v[196:197]
	v_add_f32_e32 v22, v194, v195
	v_add_f32_e32 v38, v196, v197
	s_waitcnt lgkmcnt(0)
	ds_read_b128 v[134:137], v42 offset:46848
	ds_read_b128 v[130:133], v42 offset:46592
	ds_read_b64 v[142:143], v43 offset:46080
	ds_read_b128 v[122:125], v42 offset:46080
	ds_read_b128 v[126:129], v42 offset:46336
	ds_read_b128 v[138:141], v42 offset:47104
	v_pk_mul_f32 v[176:177], v[2:3], v[166:167]
	v_pk_mul_f32 v[178:179], v[6:7], v[166:167]
	v_pk_fma_f32 v[176:177], v[4:5], v[168:169], v[176:177]
	v_pk_fma_f32 v[178:179], v[8:9], v[168:169], v[178:179]
	v_pk_mul_f32 v[180:181], v[162:163], v[174:175] op_sel_hi:[1,0]
	v_add_f32_e32 v198, v176, v177
	v_pk_mul_f32 v[190:191], v[162:163], v[174:175] op_sel:[0,1] op_sel_hi:[1,1]
	v_add_f32_e32 v200, v178, v179
	v_pk_mul_f32 v[188:189], v[164:165], v[174:175] op_sel_hi:[1,0]
	v_add_f32_dpp v198, v198, v198 quad_perm:[1,0,3,2] row_mask:0xf bank_mask:0xf bound_ctrl:1
	v_pk_mul_f32 v[192:193], v[164:165], v[174:175] op_sel:[0,1] op_sel_hi:[1,1]
	v_add_f32_dpp v200, v200, v200 quad_perm:[1,0,3,2] row_mask:0xf bank_mask:0xf bound_ctrl:1
	v_pk_fma_f32 v[2:3], v[2:3], v[154:155], v[180:181]
	v_add_f32_dpp v198, v198, v198 quad_perm:[2,3,0,1] row_mask:0xf bank_mask:0xf bound_ctrl:1
	v_pk_fma_f32 v[6:7], v[6:7], v[154:155], v[190:191]
	v_add_f32_dpp v200, v200, v200 quad_perm:[2,3,0,1] row_mask:0xf bank_mask:0xf bound_ctrl:1
	v_pk_fma_f32 v[4:5], v[4:5], v[156:157], v[188:189]
	v_add_f32_dpp v198, v198, v198 row_half_mirror row_mask:0xf bank_mask:0xf bound_ctrl:1
	v_pk_fma_f32 v[8:9], v[8:9], v[156:157], v[192:193]
	v_add_f32_dpp v200, v200, v200 row_half_mirror row_mask:0xf bank_mask:0xf bound_ctrl:1
	s_nop 0
	v_add_f32_dpp v198, v198, v198 row_mirror row_mask:0xf bank_mask:0xf bound_ctrl:1
	s_nop 0
	v_add_f32_dpp v200, v200, v200 row_mirror row_mask:0xf bank_mask:0xf bound_ctrl:1
	v_pk_fma_f32 v[2:3], v[158:159], v[198:199], v[2:3] op_sel_hi:[1,0,1] neg_lo:[0,1,0] neg_hi:[0,1,0]
	v_pk_fma_f32 v[4:5], v[160:161], v[198:199], v[4:5] op_sel_hi:[1,0,1] neg_lo:[0,1,0] neg_hi:[0,1,0]
	v_pk_fma_f32 v[6:7], v[158:159], v[200:201], v[6:7] op_sel_hi:[1,0,1] neg_lo:[0,1,0] neg_hi:[0,1,0]
	v_pk_fma_f32 v[8:9], v[160:161], v[200:201], v[8:9] op_sel_hi:[1,0,1] neg_lo:[0,1,0] neg_hi:[0,1,0]
	v_pk_mul_f32 v[194:195], v[172:173], v[4:5]
	v_pk_mul_f32 v[196:197], v[172:173], v[8:9]
	v_pk_fma_f32 v[194:195], v[170:171], v[2:3], v[194:195]
	v_pk_fma_f32 v[196:197], v[170:171], v[6:7], v[196:197]
	v_add_f32_e32 v23, v194, v195
	v_add_f32_e32 v39, v196, v197
	s_waitcnt lgkmcnt(0)
	ds_read_b128 v[166:169], v42 offset:48384
	ds_read_b128 v[162:165], v42 offset:48128
	ds_read_b64 v[174:175], v43 offset:47616
	ds_read_b128 v[154:157], v42 offset:47616
	ds_read_b128 v[158:161], v42 offset:47872
	ds_read_b128 v[170:173], v42 offset:48640
	v_pk_mul_f32 v[176:177], v[2:3], v[134:135]
	v_pk_mul_f32 v[178:179], v[6:7], v[134:135]
	v_pk_fma_f32 v[176:177], v[4:5], v[136:137], v[176:177]
	v_pk_fma_f32 v[178:179], v[8:9], v[136:137], v[178:179]
	v_pk_mul_f32 v[180:181], v[130:131], v[142:143] op_sel_hi:[1,0]
	v_add_f32_e32 v198, v176, v177
	v_pk_mul_f32 v[190:191], v[130:131], v[142:143] op_sel:[0,1] op_sel_hi:[1,1]
	v_add_f32_e32 v200, v178, v179
	v_pk_mul_f32 v[188:189], v[132:133], v[142:143] op_sel_hi:[1,0]
	v_add_f32_dpp v198, v198, v198 quad_perm:[1,0,3,2] row_mask:0xf bank_mask:0xf bound_ctrl:1
	v_pk_mul_f32 v[192:193], v[132:133], v[142:143] op_sel:[0,1] op_sel_hi:[1,1]
	v_add_f32_dpp v200, v200, v200 quad_perm:[1,0,3,2] row_mask:0xf bank_mask:0xf bound_ctrl:1
	v_pk_fma_f32 v[2:3], v[2:3], v[122:123], v[180:181]
	v_add_f32_dpp v198, v198, v198 quad_perm:[2,3,0,1] row_mask:0xf bank_mask:0xf bound_ctrl:1
	v_pk_fma_f32 v[6:7], v[6:7], v[122:123], v[190:191]
	v_add_f32_dpp v200, v200, v200 quad_perm:[2,3,0,1] row_mask:0xf bank_mask:0xf bound_ctrl:1
	v_pk_fma_f32 v[4:5], v[4:5], v[124:125], v[188:189]
	v_add_f32_dpp v198, v198, v198 row_half_mirror row_mask:0xf bank_mask:0xf bound_ctrl:1
	v_pk_fma_f32 v[8:9], v[8:9], v[124:125], v[192:193]
	v_add_f32_dpp v200, v200, v200 row_half_mirror row_mask:0xf bank_mask:0xf bound_ctrl:1
	s_nop 0
	v_add_f32_dpp v198, v198, v198 row_mirror row_mask:0xf bank_mask:0xf bound_ctrl:1
	s_nop 0
	v_add_f32_dpp v200, v200, v200 row_mirror row_mask:0xf bank_mask:0xf bound_ctrl:1
	v_pk_fma_f32 v[2:3], v[126:127], v[198:199], v[2:3] op_sel_hi:[1,0,1] neg_lo:[0,1,0] neg_hi:[0,1,0]
	v_pk_fma_f32 v[4:5], v[128:129], v[198:199], v[4:5] op_sel_hi:[1,0,1] neg_lo:[0,1,0] neg_hi:[0,1,0]
	v_pk_fma_f32 v[6:7], v[126:127], v[200:201], v[6:7] op_sel_hi:[1,0,1] neg_lo:[0,1,0] neg_hi:[0,1,0]
	v_pk_fma_f32 v[8:9], v[128:129], v[200:201], v[8:9] op_sel_hi:[1,0,1] neg_lo:[0,1,0] neg_hi:[0,1,0]
	v_pk_mul_f32 v[194:195], v[140:141], v[4:5]
	v_pk_mul_f32 v[196:197], v[140:141], v[8:9]
	v_pk_fma_f32 v[194:195], v[138:139], v[2:3], v[194:195]
	v_pk_fma_f32 v[196:197], v[138:139], v[6:7], v[196:197]
	v_add_f32_e32 v24, v194, v195
	v_add_f32_e32 v40, v196, v197
	s_waitcnt lgkmcnt(0)
	v_pk_mul_f32 v[176:177], v[2:3], v[166:167]
	v_pk_mul_f32 v[178:179], v[6:7], v[166:167]
	v_pk_fma_f32 v[176:177], v[4:5], v[168:169], v[176:177]
	v_pk_fma_f32 v[178:179], v[8:9], v[168:169], v[178:179]
	v_pk_mul_f32 v[180:181], v[162:163], v[174:175] op_sel_hi:[1,0]
	v_add_f32_e32 v198, v176, v177
	v_pk_mul_f32 v[190:191], v[162:163], v[174:175] op_sel:[0,1] op_sel_hi:[1,1]
	v_add_f32_e32 v200, v178, v179
	v_pk_mul_f32 v[188:189], v[164:165], v[174:175] op_sel_hi:[1,0]
	v_add_f32_dpp v198, v198, v198 quad_perm:[1,0,3,2] row_mask:0xf bank_mask:0xf bound_ctrl:1
	v_pk_mul_f32 v[192:193], v[164:165], v[174:175] op_sel:[0,1] op_sel_hi:[1,1]
	v_add_f32_dpp v200, v200, v200 quad_perm:[1,0,3,2] row_mask:0xf bank_mask:0xf bound_ctrl:1
	v_pk_fma_f32 v[2:3], v[2:3], v[154:155], v[180:181]
	v_add_f32_dpp v198, v198, v198 quad_perm:[2,3,0,1] row_mask:0xf bank_mask:0xf bound_ctrl:1
	v_pk_fma_f32 v[6:7], v[6:7], v[154:155], v[190:191]
	v_add_f32_dpp v200, v200, v200 quad_perm:[2,3,0,1] row_mask:0xf bank_mask:0xf bound_ctrl:1
	v_pk_fma_f32 v[4:5], v[4:5], v[156:157], v[188:189]
	v_add_f32_dpp v198, v198, v198 row_half_mirror row_mask:0xf bank_mask:0xf bound_ctrl:1
	v_pk_fma_f32 v[8:9], v[8:9], v[156:157], v[192:193]
	v_add_f32_dpp v200, v200, v200 row_half_mirror row_mask:0xf bank_mask:0xf bound_ctrl:1
	s_nop 0
	v_add_f32_dpp v198, v198, v198 row_mirror row_mask:0xf bank_mask:0xf bound_ctrl:1
	s_nop 0
	v_add_f32_dpp v200, v200, v200 row_mirror row_mask:0xf bank_mask:0xf bound_ctrl:1
	v_pk_fma_f32 v[2:3], v[158:159], v[198:199], v[2:3] op_sel_hi:[1,0,1] neg_lo:[0,1,0] neg_hi:[0,1,0]
	v_pk_fma_f32 v[4:5], v[160:161], v[198:199], v[4:5] op_sel_hi:[1,0,1] neg_lo:[0,1,0] neg_hi:[0,1,0]
	v_pk_fma_f32 v[6:7], v[158:159], v[200:201], v[6:7] op_sel_hi:[1,0,1] neg_lo:[0,1,0] neg_hi:[0,1,0]
	v_pk_fma_f32 v[8:9], v[160:161], v[200:201], v[8:9] op_sel_hi:[1,0,1] neg_lo:[0,1,0] neg_hi:[0,1,0]
	v_pk_mul_f32 v[194:195], v[172:173], v[4:5]
	v_pk_mul_f32 v[196:197], v[172:173], v[8:9]
	v_pk_fma_f32 v[194:195], v[170:171], v[2:3], v[194:195]
	v_pk_fma_f32 v[196:197], v[170:171], v[6:7], v[196:197]
	v_add_f32_e32 v25, v194, v195
	v_add_f32_e32 v41, v196, v197
	v_add_f32_dpp v190, v10, v10 row_mirror row_mask:0xf bank_mask:0x3
	v_add_f32_dpp v190, v18, v18 row_mirror row_mask:0xf bank_mask:0xc
	v_add_f32_dpp v191, v11, v11 row_mirror row_mask:0xf bank_mask:0x3
	v_add_f32_dpp v191, v19, v19 row_mirror row_mask:0xf bank_mask:0xc
	v_add_f32_dpp v192, v12, v12 row_mirror row_mask:0xf bank_mask:0x3
	v_add_f32_dpp v192, v20, v20 row_mirror row_mask:0xf bank_mask:0xc
	v_add_f32_dpp v193, v13, v13 row_mirror row_mask:0xf bank_mask:0x3
	v_add_f32_dpp v193, v21, v21 row_mirror row_mask:0xf bank_mask:0xc
	v_add_f32_dpp v194, v14, v14 row_mirror row_mask:0xf bank_mask:0x3
	v_add_f32_dpp v194, v22, v22 row_mirror row_mask:0xf bank_mask:0xc
	v_add_f32_dpp v195, v15, v15 row_mirror row_mask:0xf bank_mask:0x3
	v_add_f32_dpp v195, v23, v23 row_mirror row_mask:0xf bank_mask:0xc
	v_add_f32_dpp v196, v16, v16 row_mirror row_mask:0xf bank_mask:0x3
	v_add_f32_dpp v196, v24, v24 row_mirror row_mask:0xf bank_mask:0xc
	v_add_f32_dpp v197, v17, v17 row_mirror row_mask:0xf bank_mask:0x3
	v_add_f32_dpp v197, v25, v25 row_mirror row_mask:0xf bank_mask:0xc
	v_add_f32_dpp v202, v190, v190 row_half_mirror row_mask:0xf bank_mask:0x5
	v_add_f32_dpp v202, v194, v194 row_half_mirror row_mask:0xf bank_mask:0xa
	v_add_f32_dpp v203, v191, v191 row_half_mirror row_mask:0xf bank_mask:0x5
	v_add_f32_dpp v203, v195, v195 row_half_mirror row_mask:0xf bank_mask:0xa
	v_add_f32_dpp v204, v192, v192 row_half_mirror row_mask:0xf bank_mask:0x5
	v_add_f32_dpp v204, v196, v196 row_half_mirror row_mask:0xf bank_mask:0xa
	v_add_f32_dpp v205, v193, v193 row_half_mirror row_mask:0xf bank_mask:0x5
	v_add_f32_dpp v205, v197, v197 row_half_mirror row_mask:0xf bank_mask:0xa
	v_cndmask_b32_e64 v176, v202, v204, s[84:85]
	v_cndmask_b32_e64 v177, v204, v202, s[84:85]
	v_cndmask_b32_e64 v178, v203, v205, s[84:85]
	v_cndmask_b32_e64 v179, v205, v203, s[84:85]
	s_nop 1
	v_add_f32_dpp v210, v177, v176 quad_perm:[2,3,0,1] row_mask:0xf bank_mask:0xf bound_ctrl:1
	v_add_f32_dpp v211, v179, v178 quad_perm:[2,3,0,1] row_mask:0xf bank_mask:0xf bound_ctrl:1
	s_nop 0
	v_cndmask_b32_e64 v176, v210, v211, s[88:89]
	v_cndmask_b32_e64 v177, v211, v210, s[88:89]
	s_nop 1
	v_add_f32_dpp v212, v177, v176 quad_perm:[1,0,3,2] row_mask:0xf bank_mask:0xf bound_ctrl:1
	ds_write_b32 v44, v212 offset:2304
	v_add_f32_dpp v190, v26, v26 row_mirror row_mask:0xf bank_mask:0x3
	v_add_f32_dpp v190, v34, v34 row_mirror row_mask:0xf bank_mask:0xc
	v_add_f32_dpp v191, v27, v27 row_mirror row_mask:0xf bank_mask:0x3
	v_add_f32_dpp v191, v35, v35 row_mirror row_mask:0xf bank_mask:0xc
	v_add_f32_dpp v192, v28, v28 row_mirror row_mask:0xf bank_mask:0x3
	v_add_f32_dpp v192, v36, v36 row_mirror row_mask:0xf bank_mask:0xc
	v_add_f32_dpp v193, v29, v29 row_mirror row_mask:0xf bank_mask:0x3
	v_add_f32_dpp v193, v37, v37 row_mirror row_mask:0xf bank_mask:0xc
	v_add_f32_dpp v194, v30, v30 row_mirror row_mask:0xf bank_mask:0x3
	v_add_f32_dpp v194, v38, v38 row_mirror row_mask:0xf bank_mask:0xc
	v_add_f32_dpp v195, v31, v31 row_mirror row_mask:0xf bank_mask:0x3
	v_add_f32_dpp v195, v39, v39 row_mirror row_mask:0xf bank_mask:0xc
	v_add_f32_dpp v196, v32, v32 row_mirror row_mask:0xf bank_mask:0x3
	v_add_f32_dpp v196, v40, v40 row_mirror row_mask:0xf bank_mask:0xc
	v_add_f32_dpp v197, v33, v33 row_mirror row_mask:0xf bank_mask:0x3
	v_add_f32_dpp v197, v41, v41 row_mirror row_mask:0xf bank_mask:0xc
	v_add_f32_dpp v202, v190, v190 row_half_mirror row_mask:0xf bank_mask:0x5
	v_add_f32_dpp v202, v194, v194 row_half_mirror row_mask:0xf bank_mask:0xa
	v_add_f32_dpp v203, v191, v191 row_half_mirror row_mask:0xf bank_mask:0x5
	v_add_f32_dpp v203, v195, v195 row_half_mirror row_mask:0xf bank_mask:0xa
	v_add_f32_dpp v204, v192, v192 row_half_mirror row_mask:0xf bank_mask:0x5
	v_add_f32_dpp v204, v196, v196 row_half_mirror row_mask:0xf bank_mask:0xa
	v_add_f32_dpp v205, v193, v193 row_half_mirror row_mask:0xf bank_mask:0x5
	v_add_f32_dpp v205, v197, v197 row_half_mirror row_mask:0xf bank_mask:0xa
	v_cndmask_b32_e64 v176, v202, v204, s[84:85]
	v_cndmask_b32_e64 v177, v204, v202, s[84:85]
	v_cndmask_b32_e64 v178, v203, v205, s[84:85]
	v_cndmask_b32_e64 v179, v205, v203, s[84:85]
	s_nop 1
	v_add_f32_dpp v210, v177, v176 quad_perm:[2,3,0,1] row_mask:0xf bank_mask:0xf bound_ctrl:1
	v_add_f32_dpp v211, v179, v178 quad_perm:[2,3,0,1] row_mask:0xf bank_mask:0xf bound_ctrl:1
	s_nop 0
	v_cndmask_b32_e64 v176, v210, v211, s[88:89]
	v_cndmask_b32_e64 v177, v211, v210, s[88:89]
	s_nop 1
	v_add_f32_dpp v212, v177, v176 quad_perm:[1,0,3,2] row_mask:0xf bank_mask:0xf bound_ctrl:1
	ds_write_b32 v44, v212 offset:2308
	v_xor_b32_e32 v42, 0xc000, v42
	v_xor_b32_e32 v43, 0xc000, v43
	v_xor_b32_e32 v44, 0x2000, v44
	s_branch .Lrc_join
